# retention outputs: decay-parameter loads issued together and GroupNorm-weight loads issued early (free VGPRs), on top of the pipelined ladders
# baseline (speedup 1.0000x reference)
; #define RLAS __attribute__((address_space(3)))
; #define LBAR() do { asm volatile("s_waitcnt lgkmcnt(0)" ::: "memory"); __builtin_amdgcn_s_barrier(); asm volatile("" ::: "memory"); } while (0)
; __device__ __forceinline__ void out_unit(RLAS unsigned char* L, int b, int h, int c, const bf16_t* QR, bf16_t* PR, const bf16_t* KR, const bf16_t* VR, const bf16_t* GR, const bf16_t* ST, size_t stbatch, const float* gnw, float lgf, float lgb, OutRegs& PF, bool is_first, bool has_next, int nb, int nh ...
;     ...
;     const size_t tok0 = (size_t)b * SEQ + (size_t)c * 128;
;     const int srow = tid >> 2, sqt = tid & 3;
;     const int grow = (tid >> 6) * 16 + ((tid >> 4) & 3), gch = tid & 15;
;     RLAS unsigned char* R2 = L + REG1 + REGV;
; #pragma unroll
;     for (int i = 0; i < 4; ++i) { *(RLAS u32x4*)(R2 + (grow + 4 * i) * RS + gch * 16) = PF.q[i]; *(RLAS u32x4*)(R0 + (grow + 4 * i) * RS + gch * 16) = PF.k[i]; *(RLAS u32x4*)(R1 + (grow + 4 * i) * RSV + gch * 16) = PF.v[i]; }
;     asm volatile("" ::: "memory"); __builtin_amdgcn_sched_barrier(0);
;     u32x4 sfr[4], sbr[4];
;     { const bf16_t* sf = ST + (size_t)b * stbatch + ((size_t)(0 * 4 + h) * 32 + c) * 16384 + (size_t)grow * 128 + gch * 8;
;       const bf16_t* sb = ST + (size_t)b * stbatch + ((size_t)(1 * 4 + h) * 32 + c) * 16384 + (size_t)grow * 128 + gch * 8;
; #pragma unroll
;       for (int i = 0; i < 4; ++i) { sfr[i] = *(const u32x4*)(sf + (size_t)(4 * i) * 128); sbr[i] = *(const u32x4*)(sb + (size_t)(4 * i) * 128); } }
;     LBAR();
; __global__ void __launch_bounds__(NWAVES * 64, 2) mega_fwd(Args args) {
;     ...
;                 const int b = U >> 7, h = (U >> 5) & 3, c = U & 31;
;                 const float lgf = -log2f(1.f + expf(-dec_f[l * 4 + h])), lgb = -log2f(1.f + expf(-dec_b[l * 4 + h]));
;                 ret_body::out_unit(L + RING_OFF, b, h, c, QR, rep ? (bf16_t*)out + ST_BATCH / 2 + (size_t)b * (ST_BATCH / 2) : QR, KR, VR, GR, STp, stbatch, gnw + l * 512, lgf, lgb, PF, i == 0, Un >= 0, Un >> 7, (Un >> 5) & 3, Un & 31);
.LBB0_502:
	s_bfe_u32 s15, s6, 0x20005
	s_or_b32 s16, s15, s9
	v_readlane_b32 s52, v252, 10
	s_ashr_i32 s0, s6, 7
	s_and_b32 s20, s6, 31
	s_lshl_b64 s[6:7], s[16:17], 2
	v_readlane_b32 s62, v252, 20
	v_readlane_b32 s63, v252, 21
	s_add_u32 s22, s62, s6
	s_addc_u32 s23, s63, s7
	global_load_dword v2, v3, s[22:23]
	s_mov_b32 s5, 0xbfb8aa3b
	s_mov_b32 s16, 0x42ce8ed0
	s_mov_b32 s21, 0xc2b17218
	v_readlane_b32 s64, v252, 22
	v_readlane_b32 s65, v252, 23
	s_add_u32 s6, s64, s6
	s_addc_u32 s7, s65, s7
	global_load_dword v56, v3, s[6:7]
	v_mov_b32_e32 v140, v0
	v_readlane_b32 s37, v255, 0
	s_movk_i32 s33, 0x110
	v_readlane_b32 s53, v252, 11
	v_readlane_b32 s54, v252, 12
	v_readlane_b32 s55, v252, 13
	v_readlane_b32 s56, v252, 14
	v_readlane_b32 s57, v252, 15
	v_readlane_b32 s58, v252, 16
	v_readlane_b32 s59, v252, 17
	v_readlane_b32 s60, v252, 18
	v_readlane_b32 s61, v252, 19
	v_readlane_b32 s66, v252, 24
	v_readlane_b32 s67, v252, 25
	s_waitcnt vmcnt(1)
	v_mul_f32_e32 v52, 0xbfb8aa3b, v2
	v_fma_f32 v53, v2, s5, -v52
	v_rndne_f32_e32 v54, v52
	v_fmac_f32_e32 v53, 0xb2a5705f, v2
	v_sub_f32_e32 v52, v52, v54
	v_add_f32_e32 v52, v52, v53
	v_cvt_i32_f32_e32 v54, v54
	v_exp_f32_e32 v52, v52
	v_cmp_nlt_f32_e32 vcc, s16, v2
	v_ldexp_f32 v52, v52, v54
	s_nop 0
	v_cndmask_b32_e32 v52, 0, v52, vcc
	v_cmp_ngt_f32_e32 vcc, s21, v2
	s_nop 1
	v_cndmask_b32_e32 v2, v225, v52, vcc
	v_add_f32_e32 v2, 1.0, v2
	v_cmp_gt_f32_e32 vcc, s35, v2
	s_and_b64 s[22:23], vcc, exec
	s_cselect_b32 s1, 32, 0
	v_ldexp_f32 v2, v2, s1
	v_log_f32_e32 v54, v2
	v_cndmask_b32_e32 v53, 0, v226, vcc
	v_ashrrev_i32_e32 v2, 6, v140
	v_bfe_u32 v52, v140, 4, 2
	v_and_b32_e32 v148, 15, v140
	v_readfirstlane_b32 s14, v2
	v_lshl_or_b32 v144, v2, 4, v52
	v_lshlrev_b32_e32 v2, 4, v148
	v_add_u32_e32 v57, s37, v2
	v_mul_lo_u32 v58, v144, s33
	v_add_u32_e32 v52, 0, v2
	v_sub_f32_e32 v149, v54, v53
	v_add_u32_e32 v53, v57, v58
	s_movk_i32 s1, 0x140
	v_mad_u64_u32 v[54:55], s[6:7], v144, s1, v[52:53]
	v_add_u32_e32 v55, 0x440, v58
	v_add_u32_e32 v136, v52, v58
	v_add_u32_e32 v59, 0x880, v58
	ds_write_b128 v53, v[16:19]
	ds_write_b128 v136, v[4:7]
	ds_write_b128 v54, v[8:11] offset:34816
	v_add_u32_e32 v4, v57, v55
	v_add_u32_e32 v137, v52, v55
	v_add_u32_e32 v5, v57, v59
	v_add_u32_e32 v138, v52, v59
	ds_write_b128 v4, v[12:15]
	ds_write_b128 v137, v[20:23]
	ds_write_b128 v54, v[28:31] offset:36096
	ds_write_b128 v5, v[40:43]
	ds_write_b128 v138, v[32:35]
	ds_write_b128 v54, v[36:39] offset:37376
	v_add_u32_e32 v58, 0xcc0, v58
	v_add_u32_e32 v6, v57, v58
	v_add_u32_e32 v139, v52, v58
	ds_write_b128 v6, v[24:27]
	ds_write_b128 v139, v[48:51]
	ds_write_b128 v54, v[44:47] offset:38656
	v_bfe_u32 v147, v140, 5, 1
	v_lshrrev_b32_e32 v141, 2, v140
	s_waitcnt vmcnt(0)
	v_mul_f32_e32 v4, 0xbfb8aa3b, v56
	v_fma_f32 v5, v56, s5, -v4
	v_rndne_f32_e32 v7, v4
	v_fmac_f32_e32 v5, 0xb2a5705f, v56
	v_sub_f32_e32 v4, v4, v7
	v_add_f32_e32 v4, v4, v5
	v_cvt_i32_f32_e32 v7, v7
	v_exp_f32_e32 v4, v4
	v_cmp_nlt_f32_e32 vcc, s16, v56
	v_ldexp_f32 v4, v4, v7
	s_nop 0
	v_cndmask_b32_e32 v4, 0, v4, vcc
	v_cmp_ngt_f32_e32 vcc, s21, v56
	s_nop 1
	v_cndmask_b32_e32 v4, v225, v4, vcc
	v_add_f32_e32 v4, 1.0, v4
	v_cmp_gt_f32_e32 vcc, s35, v4
	s_and_b64 s[6:7], vcc, exec
	s_cselect_b32 s5, 32, 0
	s_ashr_i32 s1, s0, 31
	v_ldexp_f32 v4, v4, s5
	s_lshl_b64 s[4:5], s[0:1], s4
	s_ashr_i32 s21, s27, 7
	s_bfe_u32 s22, s27, 0x20005
	s_and_b32 s23, s27, 31
	s_lshl_b32 s16, s20, 7
	s_lshl_b64 s[6:7], s[0:1], 12
	s_lshl_b64 s[4:5], s[4:5], 1
	v_readlane_b32 s1, v253, 33
	s_add_u32 s1, s1, s4
	v_readlane_b32 s4, v253, 32
	s_addc_u32 s4, s4, s5
	s_lshl_b32 s5, s20, 15
	s_lshl_b32 s26, s15, 20
	s_or_b32 s5, s26, s5
	s_add_u32 s28, s1, s5
	s_addc_u32 s29, s4, 0
	s_lshl_b32 s1, s14, 6
	s_and_b32 s26, s1, 64
	v_log_f32_e32 v4, v4
	s_lshl_b32 s30, s14, 4
	s_lshl_b32 s1, s26, 2
	s_or_b32 s6, s6, s16
	s_lshl_b32 s16, s15, 8
	s_lshl_b32 s4, s15, 9
	s_and_b32 s14, s30, 0xffffffe0
	s_add_i32 s1, s1, 0
	s_add_u32 s4, s10, s4
	v_cndmask_b32_e32 v5, 0, v226, vcc
	s_addc_u32 s5, s11, 0
	v_sub_f32_e32 v150, v4, v5
	s_cmp_gt_i32 s27, -1
	v_ashrrev_i32_e32 v145, 31, v144
	v_lshlrev_b64 v[4:5], 8, v[144:145]
	v_lshl_add_u64 v[4:5], s[28:29], 0, v[4:5]
	v_lshl_add_u64 v[4:5], v[4:5], 0, v[2:3]
	s_mov_b32 s27, 0x400000
	v_add_co_u32_e32 v8, vcc, s27, v4
	s_mov_b64 s[28:29], 0x400000
	s_nop 0
	v_addc_co_u32_e32 v9, vcc, 0, v5, vcc
	v_lshl_add_u64 v[6:7], v[4:5], 0, s[28:29]
	global_load_dwordx4 v[72:75], v[4:5], off
	global_load_dwordx4 v[76:79], v[8:9], off
	global_load_dwordx4 v[80:83], v[4:5], off offset:1024
	global_load_dwordx4 v[84:87], v[6:7], off offset:1024
	global_load_dwordx4 v[88:91], v[4:5], off offset:2048
	global_load_dwordx4 v[92:95], v[6:7], off offset:2048
	global_load_dwordx4 v[96:99], v[4:5], off offset:3072
	global_load_dwordx4 v[128:131], v[6:7], off offset:3072
	v_mov_b32_e32 v4, s30
	s_movk_i32 s27, 0xffe0
	v_bfi_b32 v154, s27, v4, v140
	v_mul_lo_u32 v4, v154, s33
	v_lshlrev_b32_e32 v5, 4, v147
	s_waitcnt lgkmcnt(0)
	s_barrier
; #define RLAS __attribute__((address_space(3)))
; #define RMFMA(a, b, c) __builtin_amdgcn_mfma_f32_32x32x16_bf16(a, b, c, 0, 0, 0)
; __device__ __forceinline__ void out_unit(RLAS unsigned char* L, int b, int h, int c, const bf16_t* QR, bf16_t* PR, const bf16_t* KR, const bf16_t* VR, const bf16_t* GR, const bf16_t* ST, size_t stbatch, const float* gnw, float lgf, float lgb, OutRegs& PF, bool is_first, bool has_next, int nb, int nh ...
;     ...
;     bf16x8 qf[8];
; #pragma unroll
;     for (int ks = 0; ks < 8; ++ks) qf[ks] = *(const RLAS bf16x8*)(R2 + (32 * ib + r) * RS + (16 * ks + 8 * h2) * 2);
;     bf16x8 P[4][2];
;     const int iq = 32 * ib + r;
;     float cfm[3], cbp[3];
; #pragma unroll
;     for (int e = 0; e < 3; ++e) { cfm[e] = __builtin_amdgcn_exp2f(-lgf * (float)(e + 1)); cbp[e] = __builtin_amdgcn_exp2f(lgb * (float)(e + 1)); }
;     { f32x16 X[4];
; #pragma unroll
;       for (int jb = 0; jb < 4; ++jb)
; #pragma unroll
;           for (int g = 0; g < 16; ++g) X[jb][g] = 0.f;
; #pragma unroll
;       for (int ks = 0; ks < 8; ++ks) { bf16x8 a[4];
; #pragma unroll
;           for (int jb = 0; jb < 4; ++jb) a[jb] = *(const RLAS bf16x8*)(R0 + (32 * jb + r) * RS + (16 * ks + 8 * h2) * 2);
; #pragma unroll
;           for (int jb = 0; jb < 4; ++jb) X[jb] = RMFMA(a[jb], qf[ks], X[jb]); }
; #pragma unroll
;       for (int jb = 0; jb < 4; ++jb) {
; #pragma unroll
;           for (int q4 = 0; q4 < 4; ++q4) {
;               const int d0 = iq - (32 * jb + 8 * q4 + 4 * h2); const float fd = (float)d0, Ff = __builtin_amdgcn_exp2f(lgf * fd), Fb = __builtin_amdgcn_exp2f(-lgb * fd);
;               X[jb][4 * q4 + 0] *= d0 >= 0 ? Ff : Fb;             X[jb][4 * q4 + 1] *= d0 >= 1 ? Ff * cfm[0] : Fb * cbp[0];
;               X[jb][4 * q4 + 2] *= d0 >= 2 ? Ff * cfm[1] : Fb * cbp[1]; X[jb][4 * q4 + 3] *= d0 >= 3 ? Ff * cfm[2] : Fb * cbp[2]; }
	v_add3_u32 v4, s37, v4, v5
	ds_read_b128 v[68:71], v4
	ds_read_b128 v[124:127], v4 offset:32
	ds_read_b128 v[120:123], v4 offset:64
	ds_read_b128 v[116:119], v4 offset:96
	ds_read_b128 v[112:115], v4 offset:128
	ds_read_b128 v[108:111], v4 offset:160
	ds_read_b128 v[104:107], v4 offset:192
	ds_read_b128 v[100:103], v4 offset:224
	v_add_f32_e32 v4, v149, v149
	v_exp_f32_e32 v132, v4
	v_mul_f32_e32 v4, -2.0, v150
	v_and_b32_e32 v151, 31, v140
	v_exp_f32_e32 v134, v4
	v_mul_f32_e32 v4, 0x40400000, v149
	v_add_u32_e32 v152, 0, v5
	v_exp_f32_e32 v133, v4
	v_mul_f32_e32 v4, 0xc0400000, v150
	v_mad_u32_u24 v153, v151, s33, v152
	v_exp_f32_e32 v135, v4
	ds_read_b128 v[4:7], v153 offset:8704
	ds_read_b128 v[8:11], v153 offset:17408
	ds_read_b128 v[12:15], v153 offset:26112
	ds_read_b128 v[16:19], v153
	ds_read_b128 v[156:159], v153 offset:32
	s_waitcnt lgkmcnt(1)
	v_mfma_f32_32x32x16_bf16 v[52:67], v[16:19], v[68:71], 0
	ds_read_b128 v[160:163], v153 offset:8736
	ds_read_b128 v[164:167], v153 offset:17440
	ds_read_b128 v[168:171], v153 offset:26144
	v_exp_f32_e32 v143, v149
	v_exp_f32_e64 v146, -v150
	v_and_b32_e32 v142, 16, v140
	s_movk_i32 s27, 0x6000
	v_mfma_f32_32x32x16_bf16 v[36:51], v[4:7], v[68:71], 0
	v_mfma_f32_32x32x16_bf16 v[20:35], v[8:11], v[68:71], 0
	v_mfma_f32_32x32x16_bf16 v[4:19], v[12:15], v[68:71], 0
	ds_read_b128 v[172:175], v153 offset:64
	ds_read_b128 v[176:179], v153 offset:8768
	ds_read_b128 v[180:183], v153 offset:17472
	ds_read_b128 v[184:187], v153 offset:26176
	s_waitcnt lgkmcnt(7)
	v_mfma_f32_32x32x16_bf16 v[52:67], v[156:159], v[124:127], v[52:67]
	s_waitcnt lgkmcnt(6)
	v_mfma_f32_32x32x16_bf16 v[36:51], v[160:163], v[124:127], v[36:51]
	s_waitcnt lgkmcnt(5)
	v_mfma_f32_32x32x16_bf16 v[20:35], v[164:167], v[124:127], v[20:35]
	s_waitcnt lgkmcnt(4)
	v_mfma_f32_32x32x16_bf16 v[4:19], v[168:171], v[124:127], v[4:19]
	ds_read_b128 v[156:159], v153 offset:96
	ds_read_b128 v[160:163], v153 offset:8800
	ds_read_b128 v[164:167], v153 offset:17504
	ds_read_b128 v[168:171], v153 offset:26208
	s_waitcnt lgkmcnt(7)
	v_mfma_f32_32x32x16_bf16 v[52:67], v[172:175], v[120:123], v[52:67]
	s_waitcnt lgkmcnt(6)
	v_mfma_f32_32x32x16_bf16 v[36:51], v[176:179], v[120:123], v[36:51]
	s_waitcnt lgkmcnt(5)
	v_mfma_f32_32x32x16_bf16 v[20:35], v[180:183], v[120:123], v[20:35]
	s_waitcnt lgkmcnt(4)
	v_mfma_f32_32x32x16_bf16 v[4:19], v[184:187], v[120:123], v[4:19]
	ds_read_b128 v[172:175], v153 offset:128
	ds_read_b128 v[176:179], v153 offset:8832
	ds_read_b128 v[180:183], v153 offset:17536
	ds_read_b128 v[184:187], v153 offset:26240
	s_waitcnt lgkmcnt(7)
	v_mfma_f32_32x32x16_bf16 v[52:67], v[156:159], v[116:119], v[52:67]
	s_waitcnt lgkmcnt(6)
	v_mfma_f32_32x32x16_bf16 v[36:51], v[160:163], v[116:119], v[36:51]
	s_waitcnt lgkmcnt(5)
	v_mfma_f32_32x32x16_bf16 v[20:35], v[164:167], v[116:119], v[20:35]
	s_waitcnt lgkmcnt(4)
	v_mfma_f32_32x32x16_bf16 v[4:19], v[168:171], v[116:119], v[4:19]
	ds_read_b128 v[156:159], v153 offset:160
	ds_read_b128 v[160:163], v153 offset:8864
	ds_read_b128 v[164:167], v153 offset:17568
	ds_read_b128 v[168:171], v153 offset:26272
	s_waitcnt lgkmcnt(7)
	v_mfma_f32_32x32x16_bf16 v[52:67], v[172:175], v[112:115], v[52:67]
	s_waitcnt lgkmcnt(6)
	v_mfma_f32_32x32x16_bf16 v[36:51], v[176:179], v[112:115], v[36:51]
	s_waitcnt lgkmcnt(5)
	v_mfma_f32_32x32x16_bf16 v[20:35], v[180:183], v[112:115], v[20:35]
	s_waitcnt lgkmcnt(4)
	v_mfma_f32_32x32x16_bf16 v[4:19], v[184:187], v[112:115], v[4:19]
	ds_read_b128 v[172:175], v153 offset:192
	ds_read_b128 v[176:179], v153 offset:8896
	ds_read_b128 v[180:183], v153 offset:17600
	ds_read_b128 v[184:187], v153 offset:26304
	s_waitcnt lgkmcnt(7)
	v_mfma_f32_32x32x16_bf16 v[52:67], v[156:159], v[108:111], v[52:67]
	s_waitcnt lgkmcnt(6)
	v_mfma_f32_32x32x16_bf16 v[36:51], v[160:163], v[108:111], v[36:51]
	s_waitcnt lgkmcnt(5)
	v_mfma_f32_32x32x16_bf16 v[20:35], v[164:167], v[108:111], v[20:35]
	s_waitcnt lgkmcnt(4)
	v_mfma_f32_32x32x16_bf16 v[4:19], v[168:171], v[108:111], v[4:19]
	ds_read_b128 v[156:159], v153 offset:224
	ds_read_b128 v[160:163], v153 offset:8928
	ds_read_b128 v[164:167], v153 offset:17632
	ds_read_b128 v[168:171], v153 offset:26336
	s_waitcnt lgkmcnt(7)
	v_mfma_f32_32x32x16_bf16 v[52:67], v[172:175], v[104:107], v[52:67]
	s_waitcnt lgkmcnt(6)
	v_mfma_f32_32x32x16_bf16 v[36:51], v[176:179], v[104:107], v[36:51]
	s_waitcnt lgkmcnt(5)
	v_mfma_f32_32x32x16_bf16 v[20:35], v[180:183], v[104:107], v[20:35]
	s_waitcnt lgkmcnt(4)
	v_mfma_f32_32x32x16_bf16 v[4:19], v[184:187], v[104:107], v[4:19]
	v_lshlrev_b32_e32 v153, 2, v147
	v_sub_u32_e32 v147, v154, v153
	v_cvt_f32_i32_e32 v155, v147
	v_cmp_gt_i32_e32 vcc, 0, v147
	v_cmp_lt_i32_e64 s[38:39], 0, v147
	v_mul_f32_e64 v154, -v149, v155
	s_waitcnt lgkmcnt(3)
	v_mfma_f32_32x32x16_bf16 v[52:67], v[156:159], v[100:103], v[52:67]
	v_mul_f32_e32 v155, v150, v155
	v_exp_f32_e32 v154, v154
	v_exp_f32_e32 v156, v155
	v_mul_f32_e32 v155, v143, v154
	v_mul_f32_e32 v157, v146, v156
	v_cndmask_b32_e64 v159, v157, v155, s[38:39]
	v_cndmask_b32_e32 v158, v154, v156, vcc
	v_cmp_lt_i32_e32 vcc, 1, v147
	v_cmp_lt_i32_e64 s[38:39], 2, v147
	v_pk_mul_f32 v[154:155], v[132:133], v[154:155] op_sel_hi:[1,0]
	v_pk_mul_f32 v[156:157], v[134:135], v[156:157] op_sel_hi:[1,0]
	s_nop 0
	v_pk_mul_f32 v[52:53], v[158:159], v[52:53]
	v_cndmask_b32_e64 v155, v157, v155, s[38:39]
	v_cndmask_b32_e32 v154, v156, v154, vcc
	v_pk_mul_f32 v[54:55], v[154:155], v[54:55]
	v_add_u32_e32 v155, -8, v147
	v_cvt_f32_i32_e32 v156, v155
	v_cmp_gt_i32_e32 vcc, 0, v155
	v_cmp_lt_i32_e64 s[38:39], 0, v155
	s_waitcnt lgkmcnt(2)
; __device__ __forceinline__ unsigned pkbf(float lo, float hi) { const f32x2r v = {lo, hi}; return __builtin_bit_cast(unsigned, __builtin_convertvector(v, bf16x2r)); }
; __device__ __forceinline__ void out_unit(RLAS unsigned char* L, int b, int h, int c, const bf16_t* QR, bf16_t* PR, const bf16_t* KR, const bf16_t* VR, const bf16_t* GR, const bf16_t* ST, size_t stbatch, const float* gnw, float lgf, float lgb, OutRegs& PF, bool is_first, bool has_next, int nb, int nh ...
;     ...
;       for (int jb = 0; jb < 4; ++jb) {
; #pragma unroll
;           for (int q4 = 0; q4 < 4; ++q4) {
;               const int d0 = iq - (32 * jb + 8 * q4 + 4 * h2); const float fd = (float)d0, Ff = __builtin_amdgcn_exp2f(lgf * fd), Fb = __builtin_amdgcn_exp2f(-lgb * fd);
;               X[jb][4 * q4 + 0] *= d0 >= 0 ? Ff : Fb;             X[jb][4 * q4 + 1] *= d0 >= 1 ? Ff * cfm[0] : Fb * cbp[0];
;               X[jb][4 * q4 + 2] *= d0 >= 2 ? Ff * cfm[1] : Fb * cbp[1]; X[jb][4 * q4 + 3] *= d0 >= 3 ? Ff * cfm[2] : Fb * cbp[2]; }
; #pragma unroll
;           for (int s = 0; s < 2; ++s) { u32x4 pw; pw.x = pkbf(X[jb][8 * s + 0], X[jb][8 * s + 1]); pw.y = pkbf(X[jb][8 * s + 2], X[jb][8 * s + 3]); pw.z = pkbf(X[jb][8 * s + 4], X[jb][8 * s + 5]); pw.w = pkbf(X[jb][8 * s + 6], X[jb][8 * s + 7]);
;               P[jb][s] = __builtin_bit_cast(bf16x8, pw); } } }
	v_mfma_f32_32x32x16_bf16 v[36:51], v[160:163], v[100:103], v[36:51]
	v_mul_f32_e64 v154, -v149, v156
	v_mul_f32_e32 v156, v150, v156
	v_exp_f32_e32 v154, v154
	v_exp_f32_e32 v156, v156
	v_mul_f32_e32 v157, v143, v154
	v_mul_f32_e32 v158, v146, v156
	v_cndmask_b32_e64 v159, v158, v157, s[38:39]
	v_cndmask_b32_e32 v158, v154, v156, vcc
	v_pk_mul_f32 v[158:159], v[158:159], v[56:57]
	v_cmp_lt_i32_e32 vcc, 1, v155
	v_cmp_lt_i32_e64 s[38:39], 2, v155
	v_pk_mul_f32 v[56:57], v[132:133], v[154:155] op_sel_hi:[1,0]
	v_pk_mul_f32 v[154:155], v[134:135], v[156:157] op_sel_hi:[1,0]
	s_waitcnt lgkmcnt(1)
	v_mfma_f32_32x32x16_bf16 v[20:35], v[164:167], v[100:103], v[20:35]
	v_cndmask_b32_e64 v57, v155, v57, s[38:39]
	v_cndmask_b32_e32 v56, v154, v56, vcc
	v_mul_f32_e64 v154, v56, v58
	v_mul_f32_e64 v155, v57, v59
	v_add_u32_e32 v57, -16, v147
	v_cvt_f32_i32_e32 v58, v57
	v_cmp_gt_i32_e32 vcc, 0, v57
	v_cmp_lt_i32_e64 s[38:39], 0, v57
	s_waitcnt lgkmcnt(0)
	v_mfma_f32_32x32x16_bf16 v[4:19], v[168:171], v[100:103], v[4:19]
	v_mul_f32_e64 v56, -v149, v58
	v_mul_f32_e32 v58, v150, v58
	v_exp_f32_e32 v56, v56
	v_exp_f32_e32 v58, v58
	v_mul_f32_e32 v59, v143, v56
	v_mul_f32_e32 v156, v146, v58
	v_cndmask_b32_e64 v157, v156, v59, s[38:39]
	v_cndmask_b32_e32 v156, v56, v58, vcc
	v_cmp_lt_i32_e32 vcc, 1, v57
	v_cmp_lt_i32_e64 s[38:39], 2, v57
	v_pk_mul_f32 v[56:57], v[132:133], v[56:57] op_sel_hi:[1,0]
	v_pk_mul_f32 v[58:59], v[134:135], v[58:59] op_sel_hi:[1,0]
	v_pk_mul_f32 v[60:61], v[156:157], v[60:61]
	v_cndmask_b32_e64 v57, v59, v57, s[38:39]
	v_cndmask_b32_e32 v56, v58, v56, vcc
	v_pk_mul_f32 v[62:63], v[56:57], v[62:63]
	v_subrev_u32_e32 v57, 24, v147
	v_cvt_f32_i32_e32 v58, v57
	v_cmp_gt_i32_e32 vcc, 0, v57
	v_cmp_lt_i32_e64 s[38:39], 0, v57
	v_mul_f32_e64 v56, -v149, v58
	v_mul_f32_e32 v58, v150, v58
	v_exp_f32_e32 v56, v56
	v_exp_f32_e32 v58, v58
	v_mul_f32_e32 v59, v143, v56
	v_mul_f32_e32 v156, v146, v58
	v_cndmask_b32_e64 v157, v156, v59, s[38:39]
	v_cndmask_b32_e32 v156, v56, v58, vcc
	v_cmp_lt_i32_e32 vcc, 1, v57
	v_cmp_lt_i32_e64 s[38:39], 2, v57
	v_pk_mul_f32 v[56:57], v[132:133], v[56:57] op_sel_hi:[1,0]
	v_pk_mul_f32 v[58:59], v[134:135], v[58:59] op_sel_hi:[1,0]
	v_pk_mul_f32 v[64:65], v[156:157], v[64:65]
	v_cndmask_b32_e64 v57, v59, v57, s[38:39]
	v_cndmask_b32_e32 v56, v58, v56, vcc
	v_pk_mul_f32 v[66:67], v[56:57], v[66:67]
	v_cvt_pk_bf16_f32 v56, v52, v53
	v_cvt_pk_bf16_f32 v52, v60, v61
	v_subrev_u32_e32 v61, 32, v147
	v_cvt_pk_bf16_f32 v53, v62, v63
	v_cvt_f32_i32_e32 v62, v61
	v_cvt_pk_bf16_f32 v57, v54, v55
	v_cvt_pk_bf16_f32 v54, v64, v65
	v_cmp_gt_i32_e32 vcc, 0, v61
	v_mul_f32_e64 v60, -v149, v62
	v_mul_f32_e32 v62, v150, v62
	v_exp_f32_e32 v60, v60
	v_exp_f32_e32 v62, v62
	v_cmp_lt_i32_e64 s[38:39], 0, v61
	v_cvt_pk_bf16_f32 v58, v158, v159
	v_mul_f32_e32 v63, v143, v60
	v_mul_f32_e32 v64, v146, v62
	v_cndmask_b32_e64 v65, v64, v63, s[38:39]
	v_cndmask_b32_e32 v64, v60, v62, vcc
	v_cmp_lt_i32_e32 vcc, 1, v61
	v_cmp_lt_i32_e64 s[38:39], 2, v61
	v_pk_mul_f32 v[60:61], v[132:133], v[60:61] op_sel_hi:[1,0]
	v_pk_mul_f32 v[62:63], v[134:135], v[62:63] op_sel_hi:[1,0]
	v_pk_mul_f32 v[36:37], v[64:65], v[36:37]
	v_cndmask_b32_e64 v61, v63, v61, s[38:39]
	v_cndmask_b32_e32 v60, v62, v60, vcc
	v_pk_mul_f32 v[38:39], v[60:61], v[38:39]
	v_subrev_u32_e32 v61, 40, v147
	v_cvt_f32_i32_e32 v62, v61
	v_cmp_gt_i32_e32 vcc, 0, v61
	v_cmp_lt_i32_e64 s[38:39], 0, v61
	v_cvt_pk_bf16_f32 v59, v154, v155
	v_mul_f32_e64 v60, -v149, v62
	v_mul_f32_e32 v62, v150, v62
	v_exp_f32_e32 v60, v60
	v_exp_f32_e32 v62, v62
	v_cvt_pk_bf16_f32 v55, v66, v67
	v_mul_f32_e32 v63, v143, v60
	v_mul_f32_e32 v64, v146, v62
	v_cndmask_b32_e64 v65, v64, v63, s[38:39]
	v_cndmask_b32_e32 v64, v60, v62, vcc
	v_pk_mul_f32 v[64:65], v[64:65], v[40:41]
	v_cmp_lt_i32_e32 vcc, 1, v61
	v_cmp_lt_i32_e64 s[38:39], 2, v61
	v_pk_mul_f32 v[40:41], v[132:133], v[60:61] op_sel_hi:[1,0]
	v_pk_mul_f32 v[60:61], v[134:135], v[62:63] op_sel_hi:[1,0]
	s_nop 0
	v_cndmask_b32_e64 v41, v61, v41, s[38:39]
	v_cndmask_b32_e32 v40, v60, v40, vcc
	v_pk_mul_f32 v[60:61], v[40:41], v[42:43]
	v_subrev_u32_e32 v41, 48, v147
	v_cvt_f32_i32_e32 v42, v41
	v_cmp_gt_i32_e32 vcc, 0, v41
	v_cmp_lt_i32_e64 s[38:39], 0, v41
	v_mul_f32_e64 v40, -v149, v42
	v_mul_f32_e32 v42, v150, v42
	v_exp_f32_e32 v40, v40
	v_exp_f32_e32 v42, v42
	v_mul_f32_e32 v43, v143, v40
	v_mul_f32_e32 v62, v146, v42
	v_cndmask_b32_e64 v63, v62, v43, s[38:39]
	v_cndmask_b32_e32 v62, v40, v42, vcc
	v_cmp_lt_i32_e32 vcc, 1, v41
	v_cmp_lt_i32_e64 s[38:39], 2, v41
	v_pk_mul_f32 v[40:41], v[132:133], v[40:41] op_sel_hi:[1,0]
	v_pk_mul_f32 v[42:43], v[134:135], v[42:43] op_sel_hi:[1,0]
	v_pk_mul_f32 v[44:45], v[62:63], v[44:45]
	v_cndmask_b32_e64 v41, v43, v41, s[38:39]
	v_cndmask_b32_e32 v40, v42, v40, vcc
	v_pk_mul_f32 v[46:47], v[40:41], v[46:47]
	v_subrev_u32_e32 v41, 56, v147
	v_cvt_f32_i32_e32 v42, v41
	v_cmp_gt_i32_e32 vcc, 0, v41
	v_cmp_lt_i32_e64 s[38:39], 0, v41
	v_mul_f32_e64 v40, -v149, v42
	v_mul_f32_e32 v42, v150, v42
	v_exp_f32_e32 v40, v40
	v_exp_f32_e32 v42, v42
	v_mul_f32_e32 v43, v143, v40
	v_mul_f32_e32 v62, v146, v42
	v_cndmask_b32_e64 v63, v62, v43, s[38:39]
	v_cndmask_b32_e32 v62, v40, v42, vcc
	v_cmp_lt_i32_e32 vcc, 1, v41
	v_cmp_lt_i32_e64 s[38:39], 2, v41
	v_pk_mul_f32 v[40:41], v[132:133], v[40:41] op_sel_hi:[1,0]
	v_pk_mul_f32 v[42:43], v[134:135], v[42:43] op_sel_hi:[1,0]
	v_pk_mul_f32 v[48:49], v[62:63], v[48:49]
	v_cndmask_b32_e64 v41, v43, v41, s[38:39]
	v_cndmask_b32_e32 v40, v42, v40, vcc
	v_pk_mul_f32 v[50:51], v[40:41], v[50:51]
	v_cvt_pk_bf16_f32 v40, v36, v37
	v_cvt_pk_bf16_f32 v36, v44, v45
; __device__ __forceinline__ unsigned pkbf(float lo, float hi) { const f32x2r v = {lo, hi}; return __builtin_bit_cast(unsigned, __builtin_convertvector(v, bf16x2r)); }
; #define RMFMA(a, b, c) __builtin_amdgcn_mfma_f32_32x32x16_bf16(a, b, c, 0, 0, 0)
; __device__ __forceinline__ void out_unit(RLAS unsigned char* L, int b, int h, int c, const bf16_t* QR, bf16_t* PR, const bf16_t* KR, const bf16_t* VR, const bf16_t* GR, const bf16_t* ST, size_t stbatch, const float* gnw, float lgf, float lgb, OutRegs& PF, bool is_first, bool has_next, int nb, int nh ...
;     ...
;       for (int jb = 0; jb < 4; ++jb) {
; #pragma unroll
;           for (int q4 = 0; q4 < 4; ++q4) {
;               const int d0 = iq - (32 * jb + 8 * q4 + 4 * h2); const float fd = (float)d0, Ff = __builtin_amdgcn_exp2f(lgf * fd), Fb = __builtin_amdgcn_exp2f(-lgb * fd);
;               X[jb][4 * q4 + 0] *= d0 >= 0 ? Ff : Fb;             X[jb][4 * q4 + 1] *= d0 >= 1 ? Ff * cfm[0] : Fb * cbp[0];
;               X[jb][4 * q4 + 2] *= d0 >= 2 ? Ff * cfm[1] : Fb * cbp[1]; X[jb][4 * q4 + 3] *= d0 >= 3 ? Ff * cfm[2] : Fb * cbp[2]; }
; #pragma unroll
;           for (int s = 0; s < 2; ++s) { u32x4 pw; pw.x = pkbf(X[jb][8 * s + 0], X[jb][8 * s + 1]); pw.y = pkbf(X[jb][8 * s + 2], X[jb][8 * s + 3]); pw.z = pkbf(X[jb][8 * s + 4], X[jb][8 * s + 5]); pw.w = pkbf(X[jb][8 * s + 6], X[jb][8 * s + 7]);
;               P[jb][s] = __builtin_bit_cast(bf16x8, pw); } } }
;     f32x16 Z[2];
; #pragma unroll
;     for (int t = 0; t < 2; ++t)
; #pragma unroll
;         for (int g = 0; g < 16; ++g) Z[t][g] = 0.f;
;     { const int cb0 = (64 * dvh + 16 * gq + 4 * p) * 2;
; #pragma unroll
;       for (int jb = 0; jb < 4; ++jb)
; #pragma unroll
;           for (int s = 0; s < 2; ++s) { const bf16x8 v0 = trfragv(R1, 32 * jb + 16 * s + 4 * h2 + q, 8, cb0), v1 = trfragv(R1, 32 * jb + 16 * s + 4 * h2 + q, 8, cb0 + 64);
;               Z[0] = RMFMA(P[jb][s], v0, Z[0]); Z[1] = RMFMA(P[jb][s], v1, Z[1]); } }
	v_subrev_u32_e32 v45, 64, v147
	v_cvt_pk_bf16_f32 v37, v46, v47
	v_cvt_f32_i32_e32 v46, v45
	v_cvt_pk_bf16_f32 v41, v38, v39
	v_cvt_pk_bf16_f32 v38, v48, v49
	v_cmp_gt_i32_e32 vcc, 0, v45
	v_mul_f32_e64 v44, -v149, v46
	v_mul_f32_e32 v46, v150, v46
	v_exp_f32_e32 v44, v44
	v_exp_f32_e32 v46, v46
	v_cmp_lt_i32_e64 s[38:39], 0, v45
	v_cvt_pk_bf16_f32 v43, v60, v61
	v_mul_f32_e32 v47, v143, v44
	v_mul_f32_e32 v48, v146, v46
	v_cndmask_b32_e64 v49, v48, v47, s[38:39]
	v_cndmask_b32_e32 v48, v44, v46, vcc
	v_cmp_lt_i32_e32 vcc, 1, v45
	v_cmp_lt_i32_e64 s[38:39], 2, v45
	v_pk_mul_f32 v[44:45], v[132:133], v[44:45] op_sel_hi:[1,0]
	v_pk_mul_f32 v[46:47], v[134:135], v[46:47] op_sel_hi:[1,0]
	v_pk_mul_f32 v[20:21], v[48:49], v[20:21]
	v_cndmask_b32_e64 v45, v47, v45, s[38:39]
	v_cndmask_b32_e32 v44, v46, v44, vcc
	v_pk_mul_f32 v[22:23], v[44:45], v[22:23]
	v_add_u32_e32 v45, 0xffffffb8, v147
	v_cvt_f32_i32_e32 v46, v45
	v_cmp_gt_i32_e32 vcc, 0, v45
	v_cmp_lt_i32_e64 s[38:39], 0, v45
	v_cvt_pk_bf16_f32 v60, v20, v21
	v_mul_f32_e64 v44, -v149, v46
	v_mul_f32_e32 v46, v150, v46
	v_exp_f32_e32 v44, v44
	v_exp_f32_e32 v46, v46
	v_add_u32_e32 v21, 0xffffffa0, v147
	v_cvt_pk_bf16_f32 v61, v22, v23
	v_mul_f32_e32 v47, v143, v44
	v_mul_f32_e32 v48, v146, v46
	v_cndmask_b32_e64 v49, v48, v47, s[38:39]
	v_cndmask_b32_e32 v48, v44, v46, vcc
	v_cmp_lt_i32_e32 vcc, 1, v45
	v_cmp_lt_i32_e64 s[38:39], 2, v45
	v_pk_mul_f32 v[44:45], v[132:133], v[44:45] op_sel_hi:[1,0]
	v_pk_mul_f32 v[46:47], v[134:135], v[46:47] op_sel_hi:[1,0]
	v_pk_mul_f32 v[24:25], v[48:49], v[24:25]
	v_cndmask_b32_e64 v45, v47, v45, s[38:39]
	v_cndmask_b32_e32 v44, v46, v44, vcc
	v_pk_mul_f32 v[26:27], v[44:45], v[26:27]
	v_add_u32_e32 v45, 0xffffffb0, v147
	v_cvt_f32_i32_e32 v46, v45
	v_cmp_gt_i32_e32 vcc, 0, v45
	v_cmp_lt_i32_e64 s[38:39], 0, v45
	v_cvt_f32_i32_e32 v22, v21
	v_mul_f32_e64 v44, -v149, v46
	v_mul_f32_e32 v46, v150, v46
	v_exp_f32_e32 v44, v44
	v_exp_f32_e32 v46, v46
	v_mul_f32_e64 v20, -v149, v22
	v_mul_f32_e32 v22, v150, v22
	v_mul_f32_e32 v47, v143, v44
	v_mul_f32_e32 v48, v146, v46
	v_cndmask_b32_e64 v49, v48, v47, s[38:39]
	v_cndmask_b32_e32 v48, v44, v46, vcc
	v_cmp_lt_i32_e32 vcc, 1, v45
	v_cmp_lt_i32_e64 s[38:39], 2, v45
	v_pk_mul_f32 v[44:45], v[132:133], v[44:45] op_sel_hi:[1,0]
	v_pk_mul_f32 v[46:47], v[134:135], v[46:47] op_sel_hi:[1,0]
	v_exp_f32_e32 v20, v20
	v_cndmask_b32_e64 v45, v47, v45, s[38:39]
	v_cndmask_b32_e32 v44, v46, v44, vcc
	v_pk_mul_f32 v[30:31], v[44:45], v[30:31]
	v_add_u32_e32 v45, 0xffffffa8, v147
	v_cvt_f32_i32_e32 v46, v45
	v_exp_f32_e32 v22, v22
	v_pk_mul_f32 v[28:29], v[48:49], v[28:29]
	v_cmp_gt_i32_e32 vcc, 0, v45
	v_mul_f32_e64 v44, -v149, v46
	v_mul_f32_e32 v46, v150, v46
	v_exp_f32_e32 v44, v44
	v_exp_f32_e32 v46, v46
	v_cmp_lt_i32_e64 s[38:39], 0, v45
	v_cvt_pk_bf16_f32 v62, v24, v25
	v_mul_f32_e32 v47, v143, v44
	v_mul_f32_e32 v48, v146, v46
	v_cndmask_b32_e64 v49, v48, v47, s[38:39]
	v_cndmask_b32_e32 v48, v44, v46, vcc
	v_cmp_lt_i32_e32 vcc, 1, v45
	v_cmp_lt_i32_e64 s[38:39], 2, v45
	v_pk_mul_f32 v[44:45], v[132:133], v[44:45] op_sel_hi:[1,0]
	v_pk_mul_f32 v[46:47], v[134:135], v[46:47] op_sel_hi:[1,0]
	v_mul_f32_e32 v23, v143, v20
	v_cndmask_b32_e64 v45, v47, v45, s[38:39]
	v_cndmask_b32_e32 v44, v46, v44, vcc
	v_mul_f32_e32 v24, v146, v22
	v_cmp_gt_i32_e32 vcc, 0, v21
	v_cmp_lt_i32_e64 s[38:39], 0, v21
	v_cvt_pk_bf16_f32 v42, v64, v65
	v_cvt_pk_bf16_f32 v39, v50, v51
	v_cndmask_b32_e64 v25, v24, v23, s[38:39]
	v_cndmask_b32_e32 v24, v20, v22, vcc
	v_cmp_lt_i32_e32 vcc, 1, v21
	v_cmp_lt_i32_e64 s[38:39], 2, v21
	v_pk_mul_f32 v[20:21], v[132:133], v[20:21] op_sel_hi:[1,0]
	v_pk_mul_f32 v[22:23], v[134:135], v[22:23] op_sel_hi:[1,0]
	v_pk_mul_f32 v[4:5], v[24:25], v[4:5]
	v_cndmask_b32_e64 v21, v23, v21, s[38:39]
	v_cndmask_b32_e32 v20, v22, v20, vcc
	v_pk_mul_f32 v[6:7], v[20:21], v[6:7]
	v_add_u32_e32 v21, 0xffffff98, v147
	v_cvt_f32_i32_e32 v22, v21
	v_cmp_gt_i32_e32 vcc, 0, v21
	v_cmp_lt_i32_e64 s[38:39], 0, v21
	v_cvt_pk_bf16_f32 v64, v4, v5
	v_mul_f32_e64 v20, -v149, v22
	v_mul_f32_e32 v22, v150, v22
	v_exp_f32_e32 v20, v20
	v_exp_f32_e32 v22, v22
	v_lshlrev_b32_e32 v4, 2, v140
	v_and_b32_e32 v4, 12, v4
	v_mul_f32_e32 v23, v143, v20
	v_mul_f32_e32 v24, v146, v22
	v_cndmask_b32_e64 v25, v24, v23, s[38:39]
	v_cndmask_b32_e32 v24, v20, v22, vcc
	v_cmp_lt_i32_e32 vcc, 1, v21
	v_cmp_lt_i32_e64 s[38:39], 2, v21
	v_pk_mul_f32 v[20:21], v[132:133], v[20:21] op_sel_hi:[1,0]
	v_pk_mul_f32 v[22:23], v[134:135], v[22:23] op_sel_hi:[1,0]
	v_pk_mul_f32 v[8:9], v[24:25], v[8:9]
	v_cndmask_b32_e64 v21, v23, v21, s[38:39]
	v_cndmask_b32_e32 v20, v22, v20, vcc
	v_pk_mul_f32 v[10:11], v[20:21], v[10:11]
	v_add_u32_e32 v21, 0xffffff90, v147
	v_cvt_f32_i32_e32 v22, v21
	v_cmp_gt_i32_e32 vcc, 0, v21
	v_cmp_lt_i32_e64 s[38:39], 0, v21
	v_or3_b32 v4, v4, v142, s26
	v_mul_f32_e64 v20, -v149, v22
	v_mul_f32_e32 v22, v150, v22
	v_exp_f32_e32 v20, v20
	v_exp_f32_e32 v22, v22
	v_and_or_b32 v5, v141, 3, v153
	v_lshlrev_b32_e32 v4, 1, v4
	v_mul_f32_e32 v23, v143, v20
	v_mul_f32_e32 v24, v146, v22
	v_cndmask_b32_e64 v25, v24, v23, s[38:39]
	v_cndmask_b32_e32 v24, v20, v22, vcc
	v_cmp_lt_i32_e32 vcc, 1, v21
	v_cmp_lt_i32_e64 s[38:39], 2, v21
	v_pk_mul_f32 v[20:21], v[132:133], v[20:21] op_sel_hi:[1,0]
	v_pk_mul_f32 v[22:23], v[134:135], v[22:23] op_sel_hi:[1,0]
	v_pk_mul_f32 v[12:13], v[24:25], v[12:13]
	v_cndmask_b32_e64 v21, v23, v21, s[38:39]
	v_cndmask_b32_e32 v20, v22, v20, vcc
	v_pk_mul_f32 v[14:15], v[20:21], v[14:15]
	v_add_u32_e32 v21, 0xffffff88, v147
	v_cvt_f32_i32_e32 v22, v21
	v_cmp_gt_i32_e32 vcc, 0, v21
	v_cmp_lt_i32_e64 s[38:39], 0, v21
	v_mul_u32_u24_e32 v5, 0x140, v5
	v_mul_f32_e64 v20, -v149, v22
	v_mul_f32_e32 v22, v150, v22
	v_exp_f32_e32 v20, v20
	v_exp_f32_e32 v22, v22
	v_add3_u32 v140, 0, v5, v4
	v_cvt_pk_bf16_f32 v65, v6, v7
	v_mul_f32_e32 v23, v143, v20
	v_mul_f32_e32 v24, v146, v22
	v_cndmask_b32_e64 v25, v24, v23, s[38:39]
	v_cndmask_b32_e32 v24, v20, v22, vcc
	v_cmp_lt_i32_e32 vcc, 1, v21
	v_cmp_lt_i32_e64 s[38:39], 2, v21
	v_pk_mul_f32 v[20:21], v[132:133], v[20:21] op_sel_hi:[1,0]
	v_pk_mul_f32 v[22:23], v[134:135], v[22:23] op_sel_hi:[1,0]
	v_pk_mul_f32 v[16:17], v[24:25], v[16:17]
	v_cndmask_b32_e64 v21, v23, v21, s[38:39]
	v_cndmask_b32_e32 v20, v22, v20, vcc
	v_pk_mul_f32 v[18:19], v[20:21], v[18:19]
	ds_read_b64_tr_b16 v[4:5], v140 offset:34816
	ds_read_b64_tr_b16 v[6:7], v140 offset:37376
	ds_read_b64_tr_b16 v[20:21], v140 offset:34880
	ds_read_b64_tr_b16 v[22:23], v140 offset:37440
	ds_read_b64_tr_b16 v[172:173], v140 offset:39936
	ds_read_b64_tr_b16 v[174:175], v140 offset:42496
	ds_read_b64_tr_b16 v[176:177], v140 offset:40000
	ds_read_b64_tr_b16 v[178:179], v140 offset:42560
	v_pk_mul_f32 v[32:33], v[48:49], v[32:33]
	v_cvt_pk_bf16_f32 v66, v8, v9
	v_cvt_pk_bf16_f32 v67, v10, v11
	v_cvt_pk_bf16_f32 v48, v12, v13
	v_cvt_pk_bf16_f32 v49, v14, v15
	v_cvt_pk_bf16_f32 v50, v16, v17
	v_cvt_pk_bf16_f32 v51, v18, v19
	s_waitcnt lgkmcnt(6)
; #define RLAS __attribute__((address_space(3)))
; #define LBAR() do { asm volatile("s_waitcnt lgkmcnt(0)" ::: "memory"); __builtin_amdgcn_s_barrier(); asm volatile("" ::: "memory"); } while (0)
; #define RMFMA(a, b, c) __builtin_amdgcn_mfma_f32_32x32x16_bf16(a, b, c, 0, 0, 0)
; __device__ __forceinline__ void out_unit(RLAS unsigned char* L, int b, int h, int c, const bf16_t* QR, bf16_t* PR, const bf16_t* KR, const bf16_t* VR, const bf16_t* GR, const bf16_t* ST, size_t stbatch, const float* gnw, float lgf, float lgb, OutRegs& PF, bool is_first, bool has_next, int nb, int nh ...
;     ...
;     { const int cb0 = (64 * dvh + 16 * gq + 4 * p) * 2;
; #pragma unroll
;       for (int jb = 0; jb < 4; ++jb)
; #pragma unroll
;           for (int s = 0; s < 2; ++s) { const bf16x8 v0 = trfragv(R1, 32 * jb + 16 * s + 4 * h2 + q, 8, cb0), v1 = trfragv(R1, 32 * jb + 16 * s + 4 * h2 + q, 8, cb0 + 64);
;               Z[0] = RMFMA(P[jb][s], v0, Z[0]); Z[1] = RMFMA(P[jb][s], v1, Z[1]); } }
;     LBAR();
; #pragma unroll
;     for (int i = 0; i < 4; ++i) { *(RLAS u32x4*)(R0 + (grow + 4 * i) * RS + gch * 16) = sfr[i]; *(RLAS u32x4*)(R1 + (grow + 4 * i) * RS + gch * 16) = sbr[i]; }
;     LBAR();
;     u32x4 gwr[4];
;     { const bf16_t* gp0 = GR + (tok0 + grow) * GRP + h * 128 + gch * 8;
; #pragma unroll
;       for (int i = 0; i < 4; ++i) gwr[i] = *(const u32x4*)(gp0 + (size_t)(4 * i) * GRP); }
;     { f32x16 Yf[2], Yb[2];
; #pragma unroll
;       for (int t = 0; t < 2; ++t)
; #pragma unroll
;           for (int g = 0; g < 16; ++g) { Yf[t][g] = 0.f; Yb[t][g] = 0.f; }
;       const int rb0 = (64 * dvh + r) * RS + 16 * h2;
; #pragma unroll
;       for (int ks = 0; ks < 8; ++ks) {
;           const bf16x8 f0 = *(const RLAS bf16x8*)(R0 + rb0 + 32 * ks), f1 = *(const RLAS bf16x8*)(R0 + rb0 + 32 * RS + 32 * ks), b0 = *(const RLAS bf16x8*)(R1 + rb0 + 32 * ks), b1 = *(const RLAS bf16x8*)(R1 + rb0 + 32 * RS + 32 * ks);
;           Yf[0] = RMFMA(qf[ks], f0, Yf[0]); Yf[1] = RMFMA(qf[ks], f1, Yf[1]); Yb[0] = RMFMA(qf[ks], b0, Yb[0]); Yb[1] = RMFMA(qf[ks], b1, Yb[1]); }
;     ...
;     f32x4 w0 = *(const f32x4*)(gnw + h * 128 + gch * 8), w1 = *(const f32x4*)(gnw + h * 128 + gch * 8 + 4);
	v_mfma_f32_32x32x16_bf16 v[4:19], v[56:59], v[4:7], 0
	v_mul_f32_e64 v34, v44, v34
	v_mul_f32_e64 v35, v45, v35
	v_cvt_pk_bf16_f32 v63, v26, v27
	v_cvt_pk_bf16_f32 v44, v28, v29
	v_cvt_pk_bf16_f32 v45, v30, v31
	v_cvt_pk_bf16_f32 v46, v32, v33
	v_cvt_pk_bf16_f32 v47, v34, v35
	v_add_u32_e32 v141, 0x8800, v140
	s_waitcnt lgkmcnt(4)
	v_mfma_f32_32x32x16_bf16 v[20:35], v[56:59], v[20:23], 0
	ds_read_b64_tr_b16 v[180:181], v140 offset:45056
	ds_read_b64_tr_b16 v[182:183], v140 offset:47616
	ds_read_b64_tr_b16 v[184:185], v140 offset:45120
	ds_read_b64_tr_b16 v[186:187], v140 offset:47680
	s_waitcnt lgkmcnt(6)
	v_mfma_f32_32x32x16_bf16 v[4:19], v[52:55], v[172:175], v[4:19]
	s_waitcnt lgkmcnt(4)
	v_mfma_f32_32x32x16_bf16 v[20:35], v[52:55], v[176:179], v[20:35]
	ds_read_b64_tr_b16 v[172:173], v140 offset:50176
	ds_read_b64_tr_b16 v[174:175], v140 offset:52736
	ds_read_b64_tr_b16 v[176:177], v140 offset:50240
	ds_read_b64_tr_b16 v[178:179], v140 offset:52800
	s_waitcnt lgkmcnt(6)
	v_mfma_f32_32x32x16_bf16 v[4:19], v[40:43], v[180:183], v[4:19]
	s_waitcnt lgkmcnt(4)
	v_mfma_f32_32x32x16_bf16 v[20:35], v[40:43], v[184:187], v[20:35]
	ds_read_b64_tr_b16 v[180:181], v140 offset:55296
	ds_read_b64_tr_b16 v[182:183], v140 offset:57856
	ds_read_b64_tr_b16 v[184:185], v140 offset:55360
	ds_read_b64_tr_b16 v[186:187], v140 offset:57920
	s_waitcnt lgkmcnt(6)
	v_mfma_f32_32x32x16_bf16 v[4:19], v[36:39], v[172:175], v[4:19]
	s_waitcnt lgkmcnt(4)
	v_mfma_f32_32x32x16_bf16 v[20:35], v[36:39], v[176:179], v[20:35]
	ds_read_b64_tr_b16 v[172:173], v140 offset:60416
	ds_read_b64_tr_b16 v[174:175], v140 offset:62976
	ds_read_b64_tr_b16 v[176:177], v140 offset:60480
	ds_read_b64_tr_b16 v[178:179], v140 offset:63040
	s_waitcnt lgkmcnt(6)
	v_mfma_f32_32x32x16_bf16 v[4:19], v[60:63], v[180:183], v[4:19]
	s_waitcnt lgkmcnt(4)
	v_mfma_f32_32x32x16_bf16 v[20:35], v[60:63], v[184:187], v[20:35]
	ds_read_b64_tr_b16 v[180:181], v141 offset:30720
	ds_read_b64_tr_b16 v[182:183], v141 offset:33280
	ds_read_b64_tr_b16 v[184:185], v141 offset:30784
	ds_read_b64_tr_b16 v[186:187], v141 offset:33344
	s_waitcnt lgkmcnt(6)
	v_mfma_f32_32x32x16_bf16 v[4:19], v[44:47], v[172:175], v[4:19]
	s_waitcnt lgkmcnt(4)
	v_mfma_f32_32x32x16_bf16 v[20:35], v[44:47], v[176:179], v[20:35]
	ds_read_b64_tr_b16 v[36:37], v141 offset:35840
	ds_read_b64_tr_b16 v[38:39], v141 offset:38400
	ds_read_b64_tr_b16 v[40:41], v141 offset:35904
	ds_read_b64_tr_b16 v[42:43], v141 offset:38464
	s_waitcnt lgkmcnt(6)
	v_mfma_f32_32x32x16_bf16 v[4:19], v[64:67], v[180:183], v[4:19]
	s_waitcnt lgkmcnt(4)
	v_mfma_f32_32x32x16_bf16 v[20:35], v[64:67], v[184:187], v[20:35]
	s_waitcnt lgkmcnt(0)
	s_barrier
	s_waitcnt vmcnt(7)
	ds_write_b128 v136, v[72:75]
	s_waitcnt vmcnt(6)
	ds_write_b128 v136, v[76:79] offset:34816
	s_waitcnt vmcnt(5)
	ds_write_b128 v137, v[80:83]
	s_waitcnt vmcnt(4)
	ds_write_b128 v137, v[84:87] offset:34816
	s_waitcnt vmcnt(3)
	ds_write_b128 v138, v[88:91]
	s_waitcnt vmcnt(2)
	ds_write_b128 v138, v[92:95] offset:34816
	s_waitcnt vmcnt(1)
	ds_write_b128 v139, v[96:99]
	s_waitcnt vmcnt(0)
	ds_write_b128 v139, v[128:131] offset:34816
	s_waitcnt lgkmcnt(0)
	s_barrier
	s_waitcnt lgkmcnt(10)
	v_mfma_f32_32x32x16_bf16 v[4:19], v[48:51], v[36:39], v[4:19]
	v_lshl_add_u64 v[36:37], s[6:7], 0, v[144:145]
	v_readlane_b32 s6, v252, 32
	v_lshlrev_b64 v[146:147], 11, v[36:37]
	v_readlane_b32 s7, v252, 33
	s_nop 1
	v_lshl_add_u64 v[36:37], s[6:7], 0, v[146:147]
	v_lshl_add_u64 v[36:37], v[36:37], 0, s[16:17]
	v_lshl_add_u64 v[36:37], v[36:37], 0, v[2:3]
	s_movk_i32 s7, 0x2000
	v_add_co_u32_e32 v38, vcc, s7, v36
	s_movk_i32 s6, 0x4000
	s_nop 0
	v_addc_co_u32_e32 v39, vcc, 0, v37, vcc
	global_load_dwordx4 v[140:143], v[36:37], off
	global_load_dwordx4 v[136:139], v[38:39], off
	v_add_co_u32_e32 v38, vcc, s6, v36
	s_waitcnt lgkmcnt(8)
	v_mfma_f32_32x32x16_bf16 v[20:35], v[48:51], v[40:43], v[20:35]
	v_addc_co_u32_e32 v39, vcc, 0, v37, vcc
	v_add_co_u32_e32 v36, vcc, s27, v36
	global_load_dwordx4 v[132:135], v[38:39], off
	s_nop 0
	v_addc_co_u32_e32 v37, vcc, 0, v37, vcc
	global_load_dwordx4 v[128:131], v[36:37], off
	v_lshlrev_b32_e32 v202, 5, v148
	global_load_dwordx4 v[188:191], v202, s[4:5] offset:16
	global_load_dwordx4 v[198:201], v202, s[4:5]
	v_or_b32_e32 v36, s26, v151
	v_mad_u32_u24 v145, v36, s33, v152
	ds_read_b128 v[36:39], v145 offset:8704
	ds_read_b128 v[72:75], v145 offset:34816
	ds_read_b128 v[76:79], v145 offset:43520
	ds_read_b128 v[40:43], v145
	ds_read_b128 v[154:157], v145 offset:32
	s_waitcnt lgkmcnt(1)
	v_mfma_f32_32x32x16_bf16 v[52:67], v[68:71], v[40:43], 0
	ds_read_b128 v[158:161], v145 offset:8736
	ds_read_b128 v[162:165], v145 offset:34848
	ds_read_b128 v[166:169], v145 offset:43552
	v_mfma_f32_32x32x16_bf16 v[36:51], v[68:71], v[36:39], 0
	v_mfma_f32_32x32x16_bf16 v[84:99], v[68:71], v[72:75], 0
	v_mfma_f32_32x32x16_bf16 v[68:83], v[68:71], v[76:79], 0
	ds_read_b128 v[172:175], v145 offset:64
	ds_read_b128 v[176:179], v145 offset:8768
	ds_read_b128 v[180:183], v145 offset:34880
	ds_read_b128 v[184:187], v145 offset:43584
	s_waitcnt lgkmcnt(7)
	v_mfma_f32_32x32x16_bf16 v[52:67], v[124:127], v[154:157], v[52:67]
	s_waitcnt lgkmcnt(6)
	v_mfma_f32_32x32x16_bf16 v[36:51], v[124:127], v[158:161], v[36:51]
	s_waitcnt lgkmcnt(5)
	v_mfma_f32_32x32x16_bf16 v[84:99], v[124:127], v[162:165], v[84:99]
	s_waitcnt lgkmcnt(4)
	v_mfma_f32_32x32x16_bf16 v[68:83], v[124:127], v[166:169], v[68:83]
	ds_read_b128 v[154:157], v145 offset:96
	ds_read_b128 v[158:161], v145 offset:8800
	ds_read_b128 v[162:165], v145 offset:34912
	ds_read_b128 v[166:169], v145 offset:43616
	s_waitcnt lgkmcnt(7)
; #define RLAS __attribute__((address_space(3)))
; #define RMFMA(a, b, c) __builtin_amdgcn_mfma_f32_32x32x16_bf16(a, b, c, 0, 0, 0)
; __device__ __forceinline__ void out_unit(RLAS unsigned char* L, int b, int h, int c, const bf16_t* QR, bf16_t* PR, const bf16_t* KR, const bf16_t* VR, const bf16_t* GR, const bf16_t* ST, size_t stbatch, const float* gnw, float lgf, float lgb, OutRegs& PF, bool is_first, bool has_next, int nb, int nh ...
;     ...
;       for (int ks = 0; ks < 8; ++ks) {
;           const bf16x8 f0 = *(const RLAS bf16x8*)(R0 + rb0 + 32 * ks), f1 = *(const RLAS bf16x8*)(R0 + rb0 + 32 * RS + 32 * ks), b0 = *(const RLAS bf16x8*)(R1 + rb0 + 32 * ks), b1 = *(const RLAS bf16x8*)(R1 + rb0 + 32 * RS + 32 * ks);
;           Yf[0] = RMFMA(qf[ks], f0, Yf[0]); Yf[1] = RMFMA(qf[ks], f1, Yf[1]); Yb[0] = RMFMA(qf[ks], b0, Yb[0]); Yb[1] = RMFMA(qf[ks], b1, Yb[1]); }
; #pragma unroll
;       for (int q4 = 0; q4 < 4; ++q4) { const int il0 = 32 * ib + 8 * q4 + 4 * h2;
;           const float sf0 = __builtin_amdgcn_exp2f(lgf * (float)(il0 + 1)), sb0 = __builtin_amdgcn_exp2f(lgb * (float)(128 - il0));
; #pragma unroll
;           for (int e = 0; e < 4; ++e) { const float sf = e ? sf0 * __builtin_amdgcn_exp2f(lgf * (float)e) : sf0, sb = e ? sb0 * __builtin_amdgcn_exp2f(-lgb * (float)e) : sb0; const int g = 4 * q4 + e;
; #pragma unroll
;               for (int t = 0; t < 2; ++t) Z[t][g] += sf * Yf[t][g] + sb * Yb[t][g]; } } }
	v_mfma_f32_32x32x16_bf16 v[52:67], v[120:123], v[172:175], v[52:67]
	s_waitcnt lgkmcnt(6)
	v_mfma_f32_32x32x16_bf16 v[36:51], v[120:123], v[176:179], v[36:51]
	s_waitcnt lgkmcnt(5)
	v_mfma_f32_32x32x16_bf16 v[84:99], v[120:123], v[180:183], v[84:99]
	s_waitcnt lgkmcnt(4)
	v_mfma_f32_32x32x16_bf16 v[68:83], v[120:123], v[184:187], v[68:83]
	ds_read_b128 v[172:175], v145 offset:128
	ds_read_b128 v[176:179], v145 offset:8832
	ds_read_b128 v[180:183], v145 offset:34944
	ds_read_b128 v[184:187], v145 offset:43648
	s_waitcnt lgkmcnt(7)
	v_mfma_f32_32x32x16_bf16 v[52:67], v[116:119], v[154:157], v[52:67]
	s_waitcnt lgkmcnt(6)
	v_mfma_f32_32x32x16_bf16 v[36:51], v[116:119], v[158:161], v[36:51]
	s_waitcnt lgkmcnt(5)
	v_mfma_f32_32x32x16_bf16 v[84:99], v[116:119], v[162:165], v[84:99]
	s_waitcnt lgkmcnt(4)
	v_mfma_f32_32x32x16_bf16 v[68:83], v[116:119], v[166:169], v[68:83]
	ds_read_b128 v[154:157], v145 offset:160
	ds_read_b128 v[158:161], v145 offset:8864
	ds_read_b128 v[162:165], v145 offset:34976
	ds_read_b128 v[166:169], v145 offset:43680
	s_waitcnt lgkmcnt(7)
	v_mfma_f32_32x32x16_bf16 v[52:67], v[112:115], v[172:175], v[52:67]
	s_waitcnt lgkmcnt(6)
	v_mfma_f32_32x32x16_bf16 v[36:51], v[112:115], v[176:179], v[36:51]
	s_waitcnt lgkmcnt(5)
	v_mfma_f32_32x32x16_bf16 v[84:99], v[112:115], v[180:183], v[84:99]
	s_waitcnt lgkmcnt(4)
	v_mfma_f32_32x32x16_bf16 v[68:83], v[112:115], v[184:187], v[68:83]
	ds_read_b128 v[172:175], v145 offset:192
	ds_read_b128 v[176:179], v145 offset:8896
	ds_read_b128 v[180:183], v145 offset:35008
	ds_read_b128 v[184:187], v145 offset:43712
	s_waitcnt lgkmcnt(7)
	v_mfma_f32_32x32x16_bf16 v[52:67], v[108:111], v[154:157], v[52:67]
	s_waitcnt lgkmcnt(6)
	v_mfma_f32_32x32x16_bf16 v[36:51], v[108:111], v[158:161], v[36:51]
	s_waitcnt lgkmcnt(5)
	v_mfma_f32_32x32x16_bf16 v[84:99], v[108:111], v[162:165], v[84:99]
	s_waitcnt lgkmcnt(4)
	v_mfma_f32_32x32x16_bf16 v[68:83], v[108:111], v[166:169], v[68:83]
	ds_read_b128 v[154:157], v145 offset:224
	ds_read_b128 v[158:161], v145 offset:8928
	ds_read_b128 v[162:165], v145 offset:35040
	ds_read_b128 v[166:169], v145 offset:43744
	s_waitcnt lgkmcnt(7)
	v_mfma_f32_32x32x16_bf16 v[52:67], v[104:107], v[172:175], v[52:67]
	s_waitcnt lgkmcnt(6)
	v_mfma_f32_32x32x16_bf16 v[36:51], v[104:107], v[176:179], v[36:51]
	s_waitcnt lgkmcnt(5)
	v_mfma_f32_32x32x16_bf16 v[84:99], v[104:107], v[180:183], v[84:99]
	s_waitcnt lgkmcnt(4)
	v_mfma_f32_32x32x16_bf16 v[68:83], v[104:107], v[184:187], v[68:83]
	s_waitcnt lgkmcnt(0)
	s_barrier
	s_waitcnt lgkmcnt(3)
	v_mfma_f32_32x32x16_bf16 v[52:67], v[100:103], v[154:157], v[52:67]
	s_waitcnt lgkmcnt(2)
	v_mfma_f32_32x32x16_bf16 v[36:51], v[100:103], v[158:161], v[36:51]
	s_waitcnt lgkmcnt(1)
	v_mfma_f32_32x32x16_bf16 v[84:99], v[100:103], v[162:165], v[84:99]
	s_waitcnt lgkmcnt(0)
	v_mfma_f32_32x32x16_bf16 v[68:83], v[100:103], v[166:169], v[68:83]
	v_or_b32_e32 v100, s14, v153
	v_sub_u32_e32 v102, 0x80, v100
	v_or_b32_e32 v101, 1, v100
	v_cvt_f32_i32_e32 v102, v102
	v_cvt_f32_i32_e32 v101, v101
	s_movk_i32 s14, 0x210
	v_mul_f32_e64 v102, -v150, v102
	v_mul_f32_e64 v101, -v149, v101
	v_exp_f32_e32 v102, v102
	v_exp_f32_e32 v101, v101
	v_mul_f32_e32 v84, v102, v84
	v_fmac_f32_e32 v84, v101, v52
	v_mul_f32_e32 v52, v102, v68
	v_exp_f32_e32 v68, v150
	v_fmac_f32_e32 v52, v101, v36
	v_exp_f32_e64 v36, -v149
	v_add_f32_e32 v4, v4, v84
	v_mul_f32_e32 v84, v68, v102
	v_add_f32_e32 v20, v20, v52
	v_mul_f32_e32 v52, v36, v101
	v_mul_f32_e32 v85, v84, v85
	v_fmac_f32_e32 v85, v52, v53
	v_mul_f32_e32 v53, v84, v69
	v_fmac_f32_e32 v53, v52, v37
	v_add_f32_e32 v21, v21, v53
	v_add_f32_e32 v53, v150, v150
	v_mul_f32_e32 v37, -2.0, v149
	v_exp_f32_e32 v53, v53
	v_exp_f32_e32 v37, v37
	v_add_f32_e32 v5, v5, v85
	v_mul_f32_e32 v69, v53, v102
	v_mul_f32_e32 v52, v37, v101
	v_mul_f32_e32 v84, v69, v86
	v_fmac_f32_e32 v84, v52, v54
	v_mul_f32_e32 v54, v69, v70
	v_fmac_f32_e32 v54, v52, v38
	v_add_f32_e32 v22, v22, v54
	v_mul_f32_e32 v54, 0x40400000, v150
	v_mul_f32_e32 v38, 0xc0400000, v149
	v_exp_f32_e32 v54, v54
	v_exp_f32_e32 v38, v38
	v_add_f32_e32 v6, v6, v84
	v_mul_f32_e32 v69, v54, v102
	v_mul_f32_e32 v52, v38, v101
	v_mul_f32_e32 v70, v69, v87
	v_fmac_f32_e32 v70, v52, v55
	v_mul_f32_e32 v55, v69, v71
	v_fmac_f32_e32 v55, v52, v39
	v_sub_u32_e32 v52, 0x78, v100
	v_or_b32_e32 v39, 9, v100
	v_cvt_f32_i32_e32 v52, v52
	v_cvt_f32_i32_e32 v39, v39
	v_add_f32_e32 v23, v23, v55
	v_add_f32_e32 v7, v7, v70
	v_mul_f32_e64 v52, -v150, v52
	v_mul_f32_e64 v39, -v149, v39
	v_exp_f32_e32 v52, v52
	v_exp_f32_e32 v39, v39
	v_mul_f32_e32 v55, v52, v88
	v_fmac_f32_e32 v55, v39, v56
	v_add_f32_e32 v8, v8, v55
	v_mul_f32_e32 v55, v52, v72
	v_fmac_f32_e32 v55, v39, v40
	v_add_f32_e32 v24, v24, v55
	v_mul_f32_e32 v55, v68, v52
	v_mul_f32_e32 v40, v36, v39
	v_mul_f32_e32 v56, v55, v89
	v_mul_f32_e32 v55, v55, v73
	v_fmac_f32_e32 v55, v40, v41
	v_mul_f32_e32 v41, v53, v52
	v_fmac_f32_e32 v56, v40, v57
	v_add_f32_e32 v25, v25, v55
	v_mul_f32_e32 v40, v37, v39
	v_mul_f32_e32 v55, v41, v90
	v_mul_f32_e32 v41, v41, v74
	v_fmac_f32_e32 v55, v40, v58
	v_fmac_f32_e32 v41, v40, v42
	v_mul_f32_e32 v40, v54, v52
	v_add_f32_e32 v26, v26, v41
	v_mul_f32_e32 v39, v38, v39
	v_mul_f32_e32 v41, v40, v91
	v_mul_f32_e32 v40, v40, v75
	v_fmac_f32_e32 v40, v39, v43
	v_add_f32_e32 v27, v27, v40
	v_sub_u32_e32 v40, 0x70, v100
	v_fmac_f32_e32 v41, v39, v59
	v_or_b32_e32 v39, 17, v100
	v_cvt_f32_i32_e32 v40, v40
	v_cvt_f32_i32_e32 v39, v39
	v_add_f32_e32 v11, v11, v41
	v_add_f32_e32 v9, v9, v56
	v_mul_f32_e64 v40, -v150, v40
	v_mul_f32_e64 v39, -v149, v39
	v_exp_f32_e32 v40, v40
	v_exp_f32_e32 v39, v39
; __device__ __forceinline__ int crow(int r,int hi){return (r&3)+8*(r>>2)+4*hi;}
; #define RLAS __attribute__((address_space(3)))
; __device__ __forceinline__ int crow(int g, int hi) { return (g & 3) + 8 * (g >> 2) + 4 * hi; }
; #define LBAR() do { asm volatile("s_waitcnt lgkmcnt(0)" ::: "memory"); __builtin_amdgcn_s_barrier(); asm volatile("" ::: "memory"); } while (0)
; __device__ __forceinline__ void out_prefetch(OutRegs& R, int b, int h, int c, const bf16_t* QR, const bf16_t* KR, const bf16_t* VR) {
;     int tid_ = threadIdx.x; asm volatile("" : "+v"(tid_));
;     const int grow = (tid_ >> 6) * 16 + ((tid_ >> 4) & 3), gch = tid_ & 15; const size_t tok0 = (size_t)b * SEQ + (size_t)c * 128;
;     const bf16_t* kp = KR + (tok0 + grow) * 512 + h * 128 + gch * 8; const bf16_t* vp = VR + (tok0 + grow) * 512 + h * 128 + gch * 8; const bf16_t* qp = QR + (tok0 + grow) * QRP + h * 128 + gch * 8;
; #pragma unroll
;     for (int i = 0; i < 4; ++i) { R.q[i] = *(const u32x4*)(qp + (size_t)(4 * i) * QRP); R.k[i] = *(const u32x4*)(kp + (size_t)(4 * i) * 512); R.v[i] = *(const u32x4*)(vp + (size_t)(4 * i) * 512); }
; }
; __device__ __forceinline__ void out_unit(RLAS unsigned char* L, int b, int h, int c, const bf16_t* QR, bf16_t* PR, const bf16_t* KR, const bf16_t* VR, const bf16_t* GR, const bf16_t* ST, size_t stbatch, const float* gnw, float lgf, float lgb, OutRegs& PF, bool is_first, bool has_next, int nb, int nh ...
;     ...
;     LBAR();
;     { RLAS float* Os = (RLAS float*)L;
; #pragma unroll
;       for (int t = 0; t < 2; ++t)
; #pragma unroll
;           for (int g = 0; g < 16; ++g) Os[(32 * ib + crow(g, h2)) * OS + 64 * dvh + 32 * t + r] = Z[t][g]; }
;     LBAR();
;     asm volatile("" ::: "memory"); __builtin_amdgcn_sched_barrier(0);
;     f32x4 w0 = *(const f32x4*)(gnw + h * 128 + gch * 8), w1 = *(const f32x4*)(gnw + h * 128 + gch * 8 + 4);
;     asm volatile("" : "+v"(w0), "+v"(w1));
;     out_prefetch(PF, has_next ? nb : b, has_next ? nh : h, has_next ? nc : c, QR, KR, VR);
;     { const int cb = h * 128 + gch * 8;
;       f32x4 o[4][2]; float sm[4], vq[4];
; #pragma unroll
;       for (int i = 0; i < 4; ++i) { const RLAS float* Os = (const RLAS float*)L + (grow + 4 * i) * OS + gch * 8; o[i][0] = *(const RLAS f32x4*)Os; o[i][1] = *(const RLAS f32x4*)(Os + 4);
	v_add_f32_e32 v10, v10, v55
	v_mul_f32_e32 v41, v40, v92
	v_fmac_f32_e32 v41, v39, v60
	v_add_f32_e32 v12, v12, v41
	v_mul_f32_e32 v41, v40, v76
	v_fmac_f32_e32 v41, v39, v44
	v_mul_f32_e32 v42, v68, v40
	v_add_f32_e32 v28, v28, v41
	v_mul_f32_e32 v41, v36, v39
	v_mul_f32_e32 v43, v42, v93
	v_mul_f32_e32 v42, v42, v77
	v_fmac_f32_e32 v42, v41, v45
	v_fmac_f32_e32 v43, v41, v61
	v_add_f32_e32 v29, v29, v42
	v_mul_f32_e32 v42, v53, v40
	v_add_f32_e32 v13, v13, v43
	v_mul_f32_e32 v41, v37, v39
	v_mul_f32_e32 v43, v42, v94
	v_mul_f32_e32 v42, v42, v78
	v_mul_f32_e32 v40, v54, v40
	v_fmac_f32_e32 v43, v41, v62
	v_fmac_f32_e32 v42, v41, v46
	v_mul_f32_e32 v39, v38, v39
	v_mul_f32_e32 v41, v40, v95
	v_mul_f32_e32 v40, v40, v79
	v_fmac_f32_e32 v40, v39, v47
	v_add_f32_e32 v31, v31, v40
	v_sub_u32_e32 v40, 0x68, v100
	v_fmac_f32_e32 v41, v39, v63
	v_or_b32_e32 v39, 25, v100
	v_cvt_f32_i32_e32 v40, v40
	v_cvt_f32_i32_e32 v39, v39
	v_add_f32_e32 v15, v15, v41
	v_add_f32_e32 v30, v30, v42
	v_mul_f32_e64 v40, -v150, v40
	v_mul_f32_e64 v39, -v149, v39
	v_exp_f32_e32 v40, v40
	v_exp_f32_e32 v39, v39
	v_add_f32_e32 v14, v14, v43
	v_mul_f32_e32 v41, v40, v96
	v_fmac_f32_e32 v41, v39, v64
	v_add_f32_e32 v16, v16, v41
	v_mul_f32_e32 v41, v40, v80
	v_fmac_f32_e32 v41, v39, v48
	v_add_f32_e32 v32, v32, v41
	v_mul_f32_e32 v41, v68, v40
	v_mul_f32_e32 v36, v36, v39
	v_mul_f32_e32 v42, v41, v97
	v_mul_f32_e32 v41, v41, v81
	v_fmac_f32_e32 v42, v36, v65
	v_fmac_f32_e32 v41, v36, v49
	v_mul_f32_e32 v36, v37, v39
	v_mul_f32_e32 v37, v53, v40
	v_add_f32_e32 v33, v33, v41
	v_mul_f32_e32 v41, v37, v98
	v_mul_f32_e32 v37, v37, v82
	v_fmac_f32_e32 v37, v36, v50
	v_add_f32_e32 v34, v34, v37
	v_mul_f32_e32 v37, v54, v40
	v_fmac_f32_e32 v41, v36, v66
	v_mul_f32_e32 v36, v38, v39
	v_mul_f32_e32 v38, v37, v99
	v_mul_f32_e32 v37, v37, v83
	v_fmac_f32_e32 v37, v36, v51
	v_fmac_f32_e32 v38, v36, v67
	v_add_f32_e32 v35, v35, v37
	v_lshlrev_b32_e32 v36, 2, v151
	v_mul_lo_u32 v37, v100, s14
	v_add3_u32 v36, s1, v36, v37
	ds_write2_b32 v36, v4, v20 offset1:32
	ds_write2_b32 v36, v5, v21 offset0:132 offset1:164
	v_add_u32_e32 v4, 0x400, v36
	ds_write2_b32 v4, v6, v22 offset0:8 offset1:40
	ds_write2_b32 v4, v7, v23 offset0:140 offset1:172
	v_add_u32_e32 v4, 0x1000, v36
	ds_write2_b32 v4, v8, v24 offset0:32 offset1:64
	ds_write2_b32 v4, v9, v25 offset0:164 offset1:196
	v_add_u32_e32 v4, 0x1400, v36
	ds_write2_b32 v4, v10, v26 offset0:40 offset1:72
	ds_write2_b32 v4, v11, v27 offset0:172 offset1:204
	v_add_u32_e32 v4, 0x2000, v36
	ds_write2_b32 v4, v12, v28 offset0:64 offset1:96
	ds_write2_b32 v4, v13, v29 offset0:196 offset1:228
	v_add_u32_e32 v4, 0x2400, v36
	ds_write2_b32 v4, v14, v30 offset0:72 offset1:104
	ds_write2_b32 v4, v15, v31 offset0:204 offset1:236
	v_add_u32_e32 v4, 0x3000, v36
	v_add_f32_e32 v17, v17, v42
	ds_write2_b32 v4, v16, v32 offset0:96 offset1:128
	v_add_u32_e32 v4, 0x3200, v36
	v_add_f32_e32 v18, v18, v41
	ds_write2_b32 v4, v17, v33 offset0:100 offset1:132
	v_add_u32_e32 v4, 0x3400, v36
	v_add_f32_e32 v19, v19, v38
	ds_write2_b32 v4, v18, v34 offset0:104 offset1:136
	v_add_u32_e32 v4, 0x3600, v36
	ds_write2_b32 v4, v19, v35 offset0:108 offset1:140
	s_waitcnt lgkmcnt(0)
	s_barrier
	v_lshlrev_b32_e32 v60, 5, v148
	s_cselect_b32 s0, s21, s0
	v_mov_b32_e32 v10, v0
	s_cselect_b32 s4, s22, s15
	s_cselect_b32 s5, s23, s20
	s_ashr_i32 s1, s0, 31
	s_lshl_b64 s[0:1], s[0:1], 12
	s_lshl_b32 s5, s5, 7
	s_or_b32 s0, s0, s5
	v_mov_b32_e32 v11, v3
	v_mul_lo_u32 v61, v144, s14
	v_add3_u32 v92, 0, v60, v61
	v_or_b32_e32 v2, s16, v2
	s_add_i32 s12, s12, 1
	s_add_i32 s13, s13, s3
	s_waitcnt vmcnt(0)
	v_mov_b64_e32 v[52:53], v[188:189]
	v_mov_b64_e32 v[54:55], v[190:191]
	v_mov_b64_e32 v[56:57], v[198:199]
	v_mov_b64_e32 v[58:59], v[200:201]
	s_nop 0
	v_ashrrev_i32_e32 v4, 2, v10
	v_bfe_u32 v5, v10, 4, 2
	v_and_or_b32 v4, v4, -16, v5
	v_ashrrev_i32_e32 v5, 31, v4
	v_lshl_add_u64 v[4:5], s[0:1], 0, v[4:5]
	v_lshlrev_b64 v[6:7], 10, v[4:5]
	v_lshlrev_b64 v[4:5], 11, v[4:5]
	s_lshl_b32 s0, s4, 8
	s_mov_b32 s1, s17
	v_lshlrev_b32_e32 v10, 4, v10
	v_lshl_add_u64 v[4:5], s[82:83], 0, v[4:5]
	v_and_b32_e32 v10, 0xf0, v10
	v_lshl_add_u64 v[4:5], v[4:5], 0, s[0:1]
	v_lshl_add_u64 v[8:9], s[92:93], 0, v[6:7]
	v_readlane_b32 s4, v252, 30
	v_lshl_add_u64 v[24:25], v[4:5], 0, v[10:11]
	v_lshl_add_u64 v[8:9], v[8:9], 0, s[0:1]
	v_readlane_b32 s5, v252, 31
	v_add_co_u32_e32 v12, vcc, s7, v24
	v_lshl_add_u64 v[44:45], v[8:9], 0, v[10:11]
	v_lshl_add_u64 v[6:7], s[4:5], 0, v[6:7]
	v_addc_co_u32_e32 v13, vcc, 0, v25, vcc
	v_lshl_add_u64 v[6:7], v[6:7], 0, s[0:1]
	v_add_co_u32_e32 v26, vcc, s7, v44
	v_lshl_add_u64 v[46:47], v[6:7], 0, v[10:11]
	s_nop 0
	v_addc_co_u32_e32 v27, vcc, 0, v45, vcc
	v_add_co_u32_e32 v36, vcc, s7, v46
	global_load_dwordx4 v[16:19], v[24:25], off
	global_load_dwordx4 v[4:7], v[44:45], off
	global_load_dwordx4 v[8:11], v[46:47], off
	v_addc_co_u32_e32 v37, vcc, 0, v47, vcc
	v_add_co_u32_e32 v32, vcc, s6, v24
	s_movk_i32 s0, 0x3000
	s_nop 0
	v_addc_co_u32_e32 v33, vcc, 0, v25, vcc
	v_add_co_u32_e32 v24, vcc, s27, v24
	global_load_dwordx4 v[12:15], v[12:13], off
	s_nop 0
	v_addc_co_u32_e32 v25, vcc, 0, v25, vcc
	v_add_co_u32_e32 v44, vcc, s0, v44
	global_load_dwordx4 v[20:23], v[26:27], off offset:-4096
	s_nop 0
	v_addc_co_u32_e32 v45, vcc, 0, v45, vcc
	global_load_dwordx4 v[28:31], v[36:37], off offset:-4096
	global_load_dwordx4 v[40:43], v[32:33], off
	s_nop 0
	global_load_dwordx4 v[32:35], v[26:27], off
	s_nop 0
	global_load_dwordx4 v[36:39], v[36:37], off
	s_nop 0
	global_load_dwordx4 v[24:27], v[24:25], off
	s_nop 0
	global_load_dwordx4 v[48:51], v[44:45], off
	v_add_co_u32_e32 v44, vcc, s0, v46
	s_mov_b32 s0, 0x358637bd
	s_nop 0
	v_addc_co_u32_e32 v45, vcc, 0, v47, vcc
	global_load_dwordx4 v[44:47], v[44:45], off
	ds_read_b128 v[80:83], v92
	ds_read_b128 v[76:79], v92 offset:16
	ds_read_b128 v[88:91], v92 offset:2112
	ds_read_b128 v[84:87], v92 offset:2128
	ds_read_b128 v[72:75], v92 offset:4224
	ds_read_b128 v[68:71], v92 offset:4240
	s_waitcnt lgkmcnt(5)
; #define RLAS __attribute__((address_space(3)))
; __device__ __forceinline__ void out_unit(RLAS unsigned char* L, int b, int h, int c, const bf16_t* QR, bf16_t* PR, const bf16_t* KR, const bf16_t* VR, const bf16_t* GR, const bf16_t* ST, size_t stbatch, const float* gnw, float lgf, float lgb, OutRegs& PF, bool is_first, bool has_next, int nb, int nh ...
;     ...
;       for (int i = 0; i < 4; ++i) { const RLAS float* Os = (const RLAS float*)L + (grow + 4 * i) * OS + gch * 8; o[i][0] = *(const RLAS f32x4*)Os; o[i][1] = *(const RLAS f32x4*)(Os + 4);
;           sm[i] = ((o[i][0][0] + o[i][0][1]) + (o[i][0][2] + o[i][0][3])) + ((o[i][1][0] + o[i][1][1]) + (o[i][1][2] + o[i][1][3])); }
; #pragma unroll
;       for (int i = 0; i < 4; ++i) sm[i] = row16_sum(sm[i]);
; #pragma unroll
;       for (int i = 0; i < 4; ++i) { const float mean = sm[i] * (1.f / 128.f); o[i][0] = o[i][0] - mean; o[i][1] = o[i][1] - mean;
;           vq[i] = ((o[i][0][0] * o[i][0][0] + o[i][0][1] * o[i][0][1]) + (o[i][0][2] * o[i][0][2] + o[i][0][3] * o[i][0][3])) + ((o[i][1][0] * o[i][1][0] + o[i][1][1] * o[i][1][1]) + (o[i][1][2] * o[i][1][2] + o[i][1][3] * o[i][1][3])); }
; #pragma unroll
;       for (int i = 0; i < 4; ++i) vq[i] = row16_sum(vq[i]);
	v_mov_b32_e32 v60, v80
	s_waitcnt lgkmcnt(4)
	v_mov_b32_e32 v61, v76
	v_mov_b32_e32 v62, v81
	v_mov_b32_e32 v63, v77
	v_pk_add_f32 v[60:61], v[60:61], v[62:63]
	v_mov_b32_e32 v62, v82
	v_mov_b32_e32 v63, v78
	v_mov_b32_e32 v64, v83
	v_mov_b32_e32 v65, v79
	v_pk_add_f32 v[62:63], v[62:63], v[64:65]
	s_waitcnt lgkmcnt(3)
	v_mov_b32_e32 v64, v91
	v_pk_add_f32 v[60:61], v[60:61], v[62:63]
	v_mov_b32_e32 v62, v89
	v_add_f32_e32 v98, v60, v61
	v_mov_b32_e32 v60, v88
	s_waitcnt lgkmcnt(2)
	v_mov_b32_e32 v61, v84
	v_mov_b32_e32 v63, v85
	v_pk_add_f32 v[60:61], v[60:61], v[62:63]
	v_mov_b32_e32 v62, v90
	v_mov_b32_e32 v63, v86
	v_mov_b32_e32 v65, v87
	v_pk_add_f32 v[62:63], v[62:63], v[64:65]
	s_waitcnt lgkmcnt(1)
	v_mov_b32_e32 v64, v75
	v_pk_add_f32 v[60:61], v[60:61], v[62:63]
	v_mov_b32_e32 v62, v73
	v_add_f32_e32 v99, v60, v61
	v_mov_b32_e32 v60, v72
	s_waitcnt lgkmcnt(0)
	v_mov_b32_e32 v61, v68
	v_mov_b32_e32 v63, v69
	v_pk_add_f32 v[60:61], v[60:61], v[62:63]
	v_mov_b32_e32 v62, v74
	v_mov_b32_e32 v63, v70
	v_mov_b32_e32 v65, v71
	v_pk_add_f32 v[62:63], v[62:63], v[64:65]
	s_nop 0
	v_pk_add_f32 v[60:61], v[60:61], v[62:63]
	s_nop 0
	v_add_f32_e32 v100, v60, v61
	ds_read_b128 v[64:67], v92 offset:6336
	ds_read_b128 v[60:63], v92 offset:6352
	s_waitcnt lgkmcnt(1)
	v_mov_b32_e32 v92, v64
	s_waitcnt lgkmcnt(0)
	v_mov_b32_e32 v93, v60
	v_mov_b32_e32 v94, v65
	v_mov_b32_e32 v95, v61
	v_pk_add_f32 v[92:93], v[92:93], v[94:95]
	v_mov_b32_e32 v94, v66
	v_mov_b32_e32 v95, v62
	v_mov_b32_e32 v96, v67
	v_mov_b32_e32 v97, v63
	v_pk_add_f32 v[94:95], v[94:95], v[96:97]
	s_nop 0
	v_pk_add_f32 v[92:93], v[92:93], v[94:95]
	v_add_f32_dpp v94, v99, v99 quad_perm:[1,0,3,2] row_mask:0xf bank_mask:0xf bound_ctrl:1
	v_add_f32_e32 v92, v92, v93
	v_add_f32_dpp v93, v98, v98 quad_perm:[1,0,3,2] row_mask:0xf bank_mask:0xf bound_ctrl:1
	v_add_f32_dpp v94, v94, v94 quad_perm:[2,3,0,1] row_mask:0xf bank_mask:0xf bound_ctrl:1
	v_add_f32_dpp v92, v92, v92 quad_perm:[1,0,3,2] row_mask:0xf bank_mask:0xf bound_ctrl:1
	v_add_f32_dpp v93, v93, v93 quad_perm:[2,3,0,1] row_mask:0xf bank_mask:0xf bound_ctrl:1
	v_add_f32_dpp v94, v94, v94 row_half_mirror row_mask:0xf bank_mask:0xf bound_ctrl:1
	v_add_f32_dpp v92, v92, v92 quad_perm:[2,3,0,1] row_mask:0xf bank_mask:0xf bound_ctrl:1
	v_add_f32_dpp v93, v93, v93 row_half_mirror row_mask:0xf bank_mask:0xf bound_ctrl:1
	v_add_f32_dpp v102, v94, v94 row_mirror row_mask:0xf bank_mask:0xf bound_ctrl:1
	v_add_f32_dpp v92, v92, v92 row_half_mirror row_mask:0xf bank_mask:0xf bound_ctrl:1
	v_add_f32_dpp v93, v93, v93 row_mirror row_mask:0xf bank_mask:0xf bound_ctrl:1
	v_fmamk_f32 v81, v93, 0xbc000000, v81
	v_fmamk_f32 v77, v93, 0xbc000000, v77
	v_fmamk_f32 v99, v93, 0xbc000000, v83
	v_fmamk_f32 v98, v93, 0xbc000000, v82
	v_fmac_f32_e32 v80, 0xbc000000, v93
	v_fmamk_f32 v97, v93, 0xbc000000, v79
	v_fmac_f32_e32 v76, 0xbc000000, v93
	v_mov_b32_e32 v82, v81
	v_mov_b32_e32 v83, v77
	v_add_f32_dpp v104, v92, v92 row_mirror row_mask:0xf bank_mask:0xf bound_ctrl:1
	v_fmamk_f32 v96, v93, 0xbc000000, v78
	v_mov_b32_e32 v78, v80
	v_mov_b32_e32 v79, v76
	v_pk_mul_f32 v[82:83], v[82:83], v[82:83]
	v_mov_b32_e32 v92, v99
	v_mov_b32_e32 v93, v97
	v_add_f32_dpp v94, v100, v100 quad_perm:[1,0,3,2] row_mask:0xf bank_mask:0xf bound_ctrl:1
	v_pk_fma_f32 v[78:79], v[78:79], v[78:79], v[82:83]
	v_mov_b32_e32 v82, v98
	v_mov_b32_e32 v83, v96
	v_pk_mul_f32 v[92:93], v[92:93], v[92:93]
	v_add_f32_dpp v94, v94, v94 quad_perm:[2,3,0,1] row_mask:0xf bank_mask:0xf bound_ctrl:1
	v_pk_fma_f32 v[82:83], v[82:83], v[82:83], v[92:93]
	v_fmamk_f32 v89, v102, 0xbc000000, v89
	v_fmamk_f32 v85, v102, 0xbc000000, v85
	v_add_f32_dpp v94, v94, v94 row_half_mirror row_mask:0xf bank_mask:0xf bound_ctrl:1
	v_pk_add_f32 v[100:101], v[78:79], v[82:83]
	v_fmamk_f32 v93, v102, 0xbc000000, v91
	v_fmac_f32_e32 v88, 0xbc000000, v102
	v_fmamk_f32 v95, v102, 0xbc000000, v87
	v_fmac_f32_e32 v84, 0xbc000000, v102
	v_mov_b32_e32 v82, v89
	v_mov_b32_e32 v83, v85
	v_add_f32_dpp v103, v94, v94 row_mirror row_mask:0xf bank_mask:0xf bound_ctrl:1
	v_fmamk_f32 v92, v102, 0xbc000000, v90
	v_fmamk_f32 v94, v102, 0xbc000000, v86
	v_mov_b32_e32 v78, v88
	v_mov_b32_e32 v79, v84
	v_pk_mul_f32 v[82:83], v[82:83], v[82:83]
	v_mov_b32_e32 v86, v93
	v_mov_b32_e32 v87, v95
	v_pk_fma_f32 v[78:79], v[78:79], v[78:79], v[82:83]
	v_mov_b32_e32 v82, v92
	v_mov_b32_e32 v83, v94
	v_pk_mul_f32 v[86:87], v[86:87], v[86:87]
	v_fmamk_f32 v73, v103, 0xbc000000, v73
	v_pk_fma_f32 v[82:83], v[82:83], v[82:83], v[86:87]
	v_fmamk_f32 v69, v103, 0xbc000000, v69
	v_pk_add_f32 v[90:91], v[78:79], v[82:83]
	v_fmamk_f32 v75, v103, 0xbc000000, v75
	v_fmac_f32_e32 v72, 0xbc000000, v103
	v_fmamk_f32 v79, v103, 0xbc000000, v71
	v_fmac_f32_e32 v68, 0xbc000000, v103
	v_mov_b32_e32 v82, v73
	v_mov_b32_e32 v83, v69
	v_fmamk_f32 v74, v103, 0xbc000000, v74
	v_fmamk_f32 v78, v103, 0xbc000000, v70
	v_mov_b32_e32 v70, v72
	v_mov_b32_e32 v71, v68
	v_pk_mul_f32 v[82:83], v[82:83], v[82:83]
	v_mov_b32_e32 v86, v75
	v_mov_b32_e32 v87, v79
	v_pk_fma_f32 v[70:71], v[70:71], v[70:71], v[82:83]
	v_mov_b32_e32 v82, v74
	v_mov_b32_e32 v83, v78
	v_pk_mul_f32 v[86:87], v[86:87], v[86:87]
	v_fmamk_f32 v65, v104, 0xbc000000, v65
	v_pk_fma_f32 v[82:83], v[82:83], v[82:83], v[86:87]
	v_fmamk_f32 v61, v104, 0xbc000000, v61
	v_pk_add_f32 v[82:83], v[70:71], v[82:83]
	v_fmamk_f32 v67, v104, 0xbc000000, v67
	v_fmac_f32_e32 v64, 0xbc000000, v104
	v_fmamk_f32 v71, v104, 0xbc000000, v63
	v_fmac_f32_e32 v60, 0xbc000000, v104
	v_mov_b32_e32 v86, v65
	v_mov_b32_e32 v87, v61
	v_fmamk_f32 v66, v104, 0xbc000000, v66
	v_fmamk_f32 v70, v104, 0xbc000000, v62
	v_mov_b32_e32 v62, v64
;       #define SILU_(x) ((x)*__builtin_amdgcn_rcpf(1.f+__builtin_amdgcn_exp2f(-1.4426950408889634f*(x))))
; __device__ __forceinline__ unsigned pkbf(float lo, float hi) { const f32x2r v = {lo, hi}; return __builtin_bit_cast(unsigned, __builtin_convertvector(v, bf16x2r)); }
; #define SILU_(x) ((x) * __builtin_amdgcn_rcpf(1.f + __builtin_amdgcn_exp2f(-1.4426950408889634f * (x))))
; __device__ __forceinline__ void out_unit(RLAS unsigned char* L, int b, int h, int c, const bf16_t* QR, bf16_t* PR, const bf16_t* KR, const bf16_t* VR, const bf16_t* GR, const bf16_t* ST, size_t stbatch, const float* gnw, float lgf, float lgb, OutRegs& PF, bool is_first, bool has_next, int nb, int nh ...
;     ...
;       for (int i = 0; i < 4; ++i) { const float mean = sm[i] * (1.f / 128.f); o[i][0] = o[i][0] - mean; o[i][1] = o[i][1] - mean;
;           vq[i] = ((o[i][0][0] * o[i][0][0] + o[i][0][1] * o[i][0][1]) + (o[i][0][2] * o[i][0][2] + o[i][0][3] * o[i][0][3])) + ((o[i][1][0] * o[i][1][0] + o[i][1][1] * o[i][1][1]) + (o[i][1][2] * o[i][1][2] + o[i][1][3] * o[i][1][3])); }
; #pragma unroll
;       for (int i = 0; i < 4; ++i) vq[i] = row16_sum(vq[i]);
;       bf16_t* op = PR + (tok0 + grow) * QRP + cb;
; #pragma unroll
;       for (int i = 0; i < 4; ++i) { const float rstd = rsqrtf(vq[i] * (1.f / 128.f) + EPS); const u32x4 gw = gwr[i];
;           const f32x4 a0 = o[i][0] * rstd * w0, a1 = o[i][1] * rstd * w1; u32x4 ow;
;     ...
;           const float g0 = __uint_as_float(gw.x << 16), g1 = __uint_as_float(gw.x & 0xffff0000u), g2 = __uint_as_float(gw.y << 16), g3 = __uint_as_float(gw.y & 0xffff0000u), g4 = __uint_as_float(gw.z << 16), g5 = __uint_as_float(gw.z & 0xffff0000u), g6 = __uint_as_float(gw.w << 16), g7 = __uint_as_float(gw.w & 0xffff0000u);
;           ow.x = pkbf(a0[0] * SILU_(g0), a0[1] * SILU_(g1)); ow.y = pkbf(a0[2] * SILU_(g2), a0[3] * SILU_(g3));
;           ow.z = pkbf(a1[0] * SILU_(g4), a1[1] * SILU_(g5)); ow.w = pkbf(a1[2] * SILU_(g6), a1[3] * SILU_(g7));
;     ...
;           *(u32x4*)(op + (size_t)(4 * i) * QRP) = ow; } }
	v_mov_b32_e32 v63, v60
	v_pk_mul_f32 v[86:87], v[86:87], v[86:87]
	v_mov_b32_e32 v102, v67
	v_mov_b32_e32 v103, v71
	v_pk_fma_f32 v[62:63], v[62:63], v[62:63], v[86:87]
	v_mov_b32_e32 v86, v66
	v_mov_b32_e32 v87, v70
	v_pk_mul_f32 v[102:103], v[102:103], v[102:103]
	s_nop 0
	v_pk_fma_f32 v[86:87], v[86:87], v[86:87], v[102:103]
	v_lshlrev_b32_e32 v102, 16, v140
	v_pk_add_f32 v[86:87], v[62:63], v[86:87]
	v_lshl_add_u64 v[62:63], s[82:83], 0, v[146:147]
	v_lshl_add_u64 v[62:63], v[62:63], 0, v[2:3]
	v_mul_f32_e32 v2, 0xbfb8aa3b, v102
	v_exp_f32_e32 v2, v2
	v_and_b32_e32 v103, 0xffff0000, v140
	v_add_f32_e32 v2, 1.0, v2
	v_rcp_f32_e32 v104, v2
	v_mul_f32_e32 v2, 0xbfb8aa3b, v103
	v_exp_f32_e32 v2, v2
	s_nop 0
	v_add_f32_e32 v2, 1.0, v2
	v_rcp_f32_e32 v105, v2
	s_nop 0
	v_pk_mul_f32 v[102:103], v[104:105], v[102:103]
	v_lshlrev_b32_e32 v104, 16, v141
	v_mul_f32_e32 v2, 0xbfb8aa3b, v104
	v_exp_f32_e32 v2, v2
	v_and_b32_e32 v105, 0xffff0000, v141
	v_add_f32_e32 v2, 1.0, v2
	v_rcp_f32_e32 v106, v2
	v_mul_f32_e32 v2, 0xbfb8aa3b, v105
	v_exp_f32_e32 v2, v2
	s_nop 0
	v_add_f32_e32 v2, 1.0, v2
	v_rcp_f32_e32 v107, v2
	s_nop 0
	v_pk_mul_f32 v[104:105], v[106:107], v[104:105]
	v_lshlrev_b32_e32 v106, 16, v142
	v_mul_f32_e32 v2, 0xbfb8aa3b, v106
	v_exp_f32_e32 v2, v2
	v_and_b32_e32 v107, 0xffff0000, v142
	v_add_f32_e32 v2, 1.0, v2
	v_rcp_f32_e32 v108, v2
	v_mul_f32_e32 v2, 0xbfb8aa3b, v107
	v_exp_f32_e32 v2, v2
	s_nop 0
	v_add_f32_e32 v2, 1.0, v2
	v_rcp_f32_e32 v109, v2
	s_nop 0
	v_pk_mul_f32 v[106:107], v[108:109], v[106:107]
	v_lshlrev_b32_e32 v108, 16, v143
	v_mul_f32_e32 v2, 0xbfb8aa3b, v108
	v_exp_f32_e32 v2, v2
	v_and_b32_e32 v109, 0xffff0000, v143
	v_add_f32_e32 v2, 1.0, v2
	v_rcp_f32_e32 v110, v2
	v_mul_f32_e32 v2, 0xbfb8aa3b, v109
	v_exp_f32_e32 v2, v2
	s_nop 0
	v_add_f32_e32 v2, 1.0, v2
	v_rcp_f32_e32 v111, v2
	s_nop 0
	v_pk_mul_f32 v[108:109], v[110:111], v[108:109]
	v_mov_b32_e32 v110, v90
	v_mov_b32_e32 v111, v100
	v_mov_b32_e32 v100, v91
	v_pk_add_f32 v[90:91], v[110:111], v[100:101]
	s_nop 1
	v_mov_b32_dpp v101, v91 quad_perm:[1,0,3,2] row_mask:0xf bank_mask:0xf bound_ctrl:1
	v_mov_b32_dpp v100, v90 quad_perm:[1,0,3,2] row_mask:0xf bank_mask:0xf bound_ctrl:1
	v_pk_add_f32 v[90:91], v[90:91], v[100:101]
	s_nop 1
	v_mov_b32_dpp v101, v91 quad_perm:[2,3,0,1] row_mask:0xf bank_mask:0xf bound_ctrl:1
	v_mov_b32_dpp v100, v90 quad_perm:[2,3,0,1] row_mask:0xf bank_mask:0xf bound_ctrl:1
	v_pk_add_f32 v[90:91], v[90:91], v[100:101]
	s_nop 1
	v_mov_b32_dpp v101, v91 row_half_mirror row_mask:0xf bank_mask:0xf bound_ctrl:1
	v_mov_b32_dpp v100, v90 row_half_mirror row_mask:0xf bank_mask:0xf bound_ctrl:1
	v_pk_add_f32 v[90:91], v[90:91], v[100:101]
	s_nop 1
	v_mov_b32_dpp v101, v91 row_mirror row_mask:0xf bank_mask:0xf bound_ctrl:1
	v_mov_b32_dpp v100, v90 row_mirror row_mask:0xf bank_mask:0xf bound_ctrl:1
	v_pk_add_f32 v[100:101], v[90:91], v[100:101]
	v_mov_b64_e32 v[90:91], s[0:1]
	s_brev_b32 s0, 60
	v_pk_fma_f32 v[100:101], v[100:101], s[0:1], v[90:91] op_sel_hi:[1,0,0]
	s_nop 0
	v_mul_f32_e32 v2, 0x4b800000, v101
	v_cmp_gt_f32_e64 s[38:39], s35, v101
	v_cmp_gt_f32_e32 vcc, s35, v100
	s_nop 0
	v_cndmask_b32_e64 v2, v101, v2, s[38:39]
	v_rsq_f32_e32 v2, v2
	s_nop 0
	v_mul_f32_e32 v101, 0x45800000, v2
	v_cndmask_b32_e64 v2, v2, v101, s[38:39]
	v_pk_mul_f32 v[80:81], v[80:81], v[2:3] op_sel_hi:[1,0]
	v_pk_mul_f32 v[98:99], v[98:99], v[2:3] op_sel_hi:[1,0]
	v_pk_mul_f32 v[76:77], v[76:77], v[2:3] op_sel_hi:[1,0]
	v_pk_mul_f32 v[96:97], v[96:97], v[2:3] op_sel_hi:[1,0]
	v_mul_f32_e32 v2, 0x4b800000, v100
	v_cndmask_b32_e32 v2, v100, v2, vcc
	v_rsq_f32_e32 v2, v2
	v_pk_mul_f32 v[80:81], v[56:57], v[80:81]
	v_pk_mul_f32 v[76:77], v[52:53], v[76:77]
	v_pk_mul_f32 v[98:99], v[58:59], v[98:99]
	v_pk_mul_f32 v[110:111], v[54:55], v[96:97]
	v_pk_mul_f32 v[80:81], v[102:103], v[80:81]
	v_pk_mul_f32 v[76:77], v[106:107], v[76:77]
	v_cvt_pk_bf16_f32 v96, v80, v81
	v_pk_mul_f32 v[80:81], v[104:105], v[98:99]
	v_cvt_pk_bf16_f32 v98, v76, v77
	v_pk_mul_f32 v[76:77], v[108:109], v[110:111]
	v_cvt_pk_bf16_f32 v97, v80, v81
	v_cvt_pk_bf16_f32 v99, v76, v77
	v_mul_f32_e32 v76, 0x45800000, v2
	v_cndmask_b32_e32 v2, v2, v76, vcc
	v_pk_mul_f32 v[80:81], v[92:93], v[2:3] op_sel_hi:[1,0]
	v_lshlrev_b32_e32 v92, 16, v136
	v_pk_mul_f32 v[76:77], v[88:89], v[2:3] op_sel_hi:[1,0]
	v_pk_mul_f32 v[84:85], v[84:85], v[2:3] op_sel_hi:[1,0]
	v_pk_mul_f32 v[88:89], v[94:95], v[2:3] op_sel_hi:[1,0]
	v_mul_f32_e32 v2, 0xbfb8aa3b, v92
	v_exp_f32_e32 v2, v2
	v_and_b32_e32 v93, 0xffff0000, v136
	v_pk_mul_f32 v[76:77], v[56:57], v[76:77]
	v_pk_mul_f32 v[80:81], v[58:59], v[80:81]
	v_add_f32_e32 v2, 1.0, v2
	v_rcp_f32_e32 v94, v2
	v_mul_f32_e32 v2, 0xbfb8aa3b, v93
	v_exp_f32_e32 v2, v2
	v_pk_mul_f32 v[84:85], v[52:53], v[84:85]
	v_pk_mul_f32 v[88:89], v[54:55], v[88:89]
	global_store_dwordx4 v[62:63], v[96:99], off
	v_add_f32_e32 v2, 1.0, v2
	v_rcp_f32_e32 v95, v2
	s_nop 0
	v_pk_mul_f32 v[92:93], v[94:95], v[92:93]
	s_nop 0
	v_pk_mul_f32 v[76:77], v[92:93], v[76:77]
	s_nop 0
	v_cvt_pk_bf16_f32 v92, v76, v77
	v_lshlrev_b32_e32 v76, 16, v137
	v_mul_f32_e32 v2, 0xbfb8aa3b, v76
	v_exp_f32_e32 v2, v2
	v_and_b32_e32 v77, 0xffff0000, v137
	v_add_f32_e32 v2, 1.0, v2
	v_rcp_f32_e32 v94, v2
	v_mul_f32_e32 v2, 0xbfb8aa3b, v77
	v_exp_f32_e32 v2, v2
	s_nop 0
	v_add_f32_e32 v2, 1.0, v2
	v_rcp_f32_e32 v95, v2
	s_nop 0
	v_pk_mul_f32 v[76:77], v[94:95], v[76:77]
	s_nop 0
	v_pk_mul_f32 v[76:77], v[76:77], v[80:81]
	s_nop 0
	v_cvt_pk_bf16_f32 v93, v76, v77
	v_lshlrev_b32_e32 v76, 16, v138
	v_mul_f32_e32 v2, 0xbfb8aa3b, v76
	v_exp_f32_e32 v2, v2
	v_and_b32_e32 v77, 0xffff0000, v138
	v_add_f32_e32 v2, 1.0, v2
;       #define SILU_(x) ((x)*__builtin_amdgcn_rcpf(1.f+__builtin_amdgcn_exp2f(-1.4426950408889634f*(x))))
; __device__ __forceinline__ unsigned pkbf(float lo, float hi) { const f32x2r v = {lo, hi}; return __builtin_bit_cast(unsigned, __builtin_convertvector(v, bf16x2r)); }
; #define LBAR() do { asm volatile("s_waitcnt lgkmcnt(0)" ::: "memory"); __builtin_amdgcn_s_barrier(); asm volatile("" ::: "memory"); } while (0)
; #define SILU_(x) ((x) * __builtin_amdgcn_rcpf(1.f + __builtin_amdgcn_exp2f(-1.4426950408889634f * (x))))
; __device__ __forceinline__ void out_unit(RLAS unsigned char* L, int b, int h, int c, const bf16_t* QR, bf16_t* PR, const bf16_t* KR, const bf16_t* VR, const bf16_t* GR, const bf16_t* ST, size_t stbatch, const float* gnw, float lgf, float lgb, OutRegs& PF, bool is_first, bool has_next, int nb, int nh ...
;     ...
;       for (int i = 0; i < 4; ++i) { const float rstd = rsqrtf(vq[i] * (1.f / 128.f) + EPS); const u32x4 gw = gwr[i];
;           const f32x4 a0 = o[i][0] * rstd * w0, a1 = o[i][1] * rstd * w1; u32x4 ow;
;     ...
;           const float g0 = __uint_as_float(gw.x << 16), g1 = __uint_as_float(gw.x & 0xffff0000u), g2 = __uint_as_float(gw.y << 16), g3 = __uint_as_float(gw.y & 0xffff0000u), g4 = __uint_as_float(gw.z << 16), g5 = __uint_as_float(gw.z & 0xffff0000u), g6 = __uint_as_float(gw.w << 16), g7 = __uint_as_float(gw.w & 0xffff0000u);
;           ow.x = pkbf(a0[0] * SILU_(g0), a0[1] * SILU_(g1)); ow.y = pkbf(a0[2] * SILU_(g2), a0[3] * SILU_(g3));
;           ow.z = pkbf(a1[0] * SILU_(g4), a1[1] * SILU_(g5)); ow.w = pkbf(a1[2] * SILU_(g6), a1[3] * SILU_(g7));
;     ...
;           *(u32x4*)(op + (size_t)(4 * i) * QRP) = ow; } }
;     LBAR();
	v_rcp_f32_e32 v80, v2
	v_mul_f32_e32 v2, 0xbfb8aa3b, v77
	v_exp_f32_e32 v2, v2
	s_nop 0
	v_add_f32_e32 v2, 1.0, v2
	v_rcp_f32_e32 v81, v2
	s_nop 0
	v_pk_mul_f32 v[76:77], v[80:81], v[76:77]
	s_nop 0
	v_pk_mul_f32 v[76:77], v[76:77], v[84:85]
	s_nop 0
	v_cvt_pk_bf16_f32 v94, v76, v77
	v_lshlrev_b32_e32 v76, 16, v139
	v_mul_f32_e32 v2, 0xbfb8aa3b, v76
	v_exp_f32_e32 v2, v2
	v_and_b32_e32 v77, 0xffff0000, v139
	v_add_f32_e32 v2, 1.0, v2
	v_rcp_f32_e32 v80, v2
	v_mul_f32_e32 v2, 0xbfb8aa3b, v77
	v_exp_f32_e32 v2, v2
	s_nop 0
	v_add_f32_e32 v2, 1.0, v2
	v_rcp_f32_e32 v81, v2
	s_nop 0
	v_pk_mul_f32 v[76:77], v[80:81], v[76:77]
	s_nop 0
	v_pk_mul_f32 v[76:77], v[76:77], v[88:89]
	s_nop 0
	v_cvt_pk_bf16_f32 v95, v76, v77
	v_add_co_u32_e32 v76, vcc, s7, v62
	s_nop 1
	v_addc_co_u32_e32 v77, vcc, 0, v63, vcc
	global_store_dwordx4 v[76:77], v[92:95], off
	v_lshlrev_b32_e32 v76, 16, v132
	v_mul_f32_e32 v2, 0xbfb8aa3b, v76
	v_exp_f32_e32 v2, v2
	v_and_b32_e32 v77, 0xffff0000, v132
	v_add_f32_e32 v2, 1.0, v2
	v_rcp_f32_e32 v80, v2
	v_mul_f32_e32 v2, 0xbfb8aa3b, v77
	v_exp_f32_e32 v2, v2
	s_nop 0
	v_add_f32_e32 v2, 1.0, v2
	v_rcp_f32_e32 v81, v2
	s_nop 0
	v_pk_mul_f32 v[76:77], v[80:81], v[76:77]
	v_lshlrev_b32_e32 v80, 16, v133
	v_mul_f32_e32 v2, 0xbfb8aa3b, v80
	v_exp_f32_e32 v2, v2
	v_and_b32_e32 v81, 0xffff0000, v133
	v_add_f32_e32 v2, 1.0, v2
	v_rcp_f32_e32 v84, v2
	v_mul_f32_e32 v2, 0xbfb8aa3b, v81
	v_exp_f32_e32 v2, v2
	s_nop 0
	v_add_f32_e32 v2, 1.0, v2
	v_rcp_f32_e32 v85, v2
	s_nop 0
	v_pk_mul_f32 v[80:81], v[84:85], v[80:81]
	v_lshlrev_b32_e32 v84, 16, v134
	v_mul_f32_e32 v2, 0xbfb8aa3b, v84
	v_exp_f32_e32 v2, v2
	v_and_b32_e32 v85, 0xffff0000, v134
	v_add_f32_e32 v2, 1.0, v2
	v_rcp_f32_e32 v88, v2
	v_mul_f32_e32 v2, 0xbfb8aa3b, v85
	v_exp_f32_e32 v2, v2
	s_nop 0
	v_add_f32_e32 v2, 1.0, v2
	v_rcp_f32_e32 v89, v2
	s_nop 0
	v_pk_mul_f32 v[84:85], v[88:89], v[84:85]
	v_lshlrev_b32_e32 v88, 16, v135
	v_mul_f32_e32 v2, 0xbfb8aa3b, v88
	v_exp_f32_e32 v2, v2
	v_and_b32_e32 v89, 0xffff0000, v135
	v_add_f32_e32 v2, 1.0, v2
	v_rcp_f32_e32 v92, v2
	v_mul_f32_e32 v2, 0xbfb8aa3b, v89
	v_exp_f32_e32 v2, v2
	s_nop 0
	v_add_f32_e32 v2, 1.0, v2
	v_rcp_f32_e32 v93, v2
	s_nop 0
	v_pk_mul_f32 v[88:89], v[92:93], v[88:89]
	v_mov_b32_e32 v92, v86
	v_mov_b32_e32 v93, v82
	v_mov_b32_e32 v82, v87
	v_pk_add_f32 v[82:83], v[92:93], v[82:83]
	s_nop 1
	v_mov_b32_dpp v87, v83 quad_perm:[1,0,3,2] row_mask:0xf bank_mask:0xf bound_ctrl:1
	v_mov_b32_dpp v86, v82 quad_perm:[1,0,3,2] row_mask:0xf bank_mask:0xf bound_ctrl:1
	v_pk_add_f32 v[82:83], v[82:83], v[86:87]
	s_nop 1
	v_mov_b32_dpp v87, v83 quad_perm:[2,3,0,1] row_mask:0xf bank_mask:0xf bound_ctrl:1
	v_mov_b32_dpp v86, v82 quad_perm:[2,3,0,1] row_mask:0xf bank_mask:0xf bound_ctrl:1
	v_pk_add_f32 v[82:83], v[82:83], v[86:87]
	s_nop 1
	v_mov_b32_dpp v87, v83 row_half_mirror row_mask:0xf bank_mask:0xf bound_ctrl:1
	v_mov_b32_dpp v86, v82 row_half_mirror row_mask:0xf bank_mask:0xf bound_ctrl:1
	v_pk_add_f32 v[82:83], v[82:83], v[86:87]
	s_nop 1
	v_mov_b32_dpp v87, v83 row_mirror row_mask:0xf bank_mask:0xf bound_ctrl:1
	v_mov_b32_dpp v86, v82 row_mirror row_mask:0xf bank_mask:0xf bound_ctrl:1
	v_pk_add_f32 v[82:83], v[82:83], v[86:87]
	s_nop 0
	v_pk_fma_f32 v[82:83], v[82:83], s[0:1], v[90:91] op_sel_hi:[1,0,0]
	s_mov_b64 s[0:1], 0
	v_mul_f32_e32 v2, 0x4b800000, v83
	v_cmp_gt_f32_e64 s[38:39], s35, v83
	v_cmp_gt_f32_e32 vcc, s35, v82
	s_nop 0
	v_cndmask_b32_e64 v2, v83, v2, s[38:39]
	v_rsq_f32_e32 v2, v2
	s_nop 0
	v_mul_f32_e32 v83, 0x45800000, v2
	v_cndmask_b32_e64 v2, v2, v83, s[38:39]
	v_pk_mul_f32 v[72:73], v[72:73], v[2:3] op_sel_hi:[1,0]
	v_pk_mul_f32 v[74:75], v[74:75], v[2:3] op_sel_hi:[1,0]
	v_pk_mul_f32 v[68:69], v[68:69], v[2:3] op_sel_hi:[1,0]
	v_pk_mul_f32 v[78:79], v[78:79], v[2:3] op_sel_hi:[1,0]
	v_mul_f32_e32 v2, 0x4b800000, v82
	v_pk_mul_f32 v[74:75], v[58:59], v[74:75]
	v_pk_mul_f32 v[72:73], v[56:57], v[72:73]
	v_pk_mul_f32 v[68:69], v[52:53], v[68:69]
	v_cndmask_b32_e32 v2, v82, v2, vcc
	v_pk_mul_f32 v[78:79], v[54:55], v[78:79]
	v_pk_mul_f32 v[72:73], v[76:77], v[72:73]
	v_pk_mul_f32 v[74:75], v[80:81], v[74:75]
	v_pk_mul_f32 v[68:69], v[84:85], v[68:69]
	v_rsq_f32_e32 v2, v2
	v_cvt_pk_bf16_f32 v72, v72, v73
	v_cvt_pk_bf16_f32 v73, v74, v75
	v_cvt_pk_bf16_f32 v74, v68, v69
	v_pk_mul_f32 v[68:69], v[88:89], v[78:79]
	s_nop 0
	v_cvt_pk_bf16_f32 v75, v68, v69
	v_add_co_u32_e64 v68, s[38:39], s6, v62
	s_nop 1
	v_addc_co_u32_e64 v69, s[38:39], 0, v63, s[38:39]
	global_store_dwordx4 v[68:69], v[72:75], off
	v_mul_f32_e32 v68, 0x45800000, v2
	v_cndmask_b32_e32 v2, v2, v68, vcc
	v_pk_mul_f32 v[64:65], v[64:65], v[2:3] op_sel_hi:[1,0]
	v_pk_mul_f32 v[60:61], v[60:61], v[2:3] op_sel_hi:[1,0]
	v_pk_mul_f32 v[56:57], v[56:57], v[64:65]
	v_pk_mul_f32 v[64:65], v[70:71], v[2:3] op_sel_hi:[1,0]
	v_pk_mul_f32 v[66:67], v[66:67], v[2:3] op_sel_hi:[1,0]
	v_pk_mul_f32 v[64:65], v[54:55], v[64:65]
	v_pk_mul_f32 v[54:55], v[52:53], v[60:61]
	v_lshlrev_b32_e32 v52, 16, v128
	v_mul_f32_e32 v2, 0xbfb8aa3b, v52
	v_exp_f32_e32 v2, v2
	v_and_b32_e32 v53, 0xffff0000, v128
	v_pk_mul_f32 v[58:59], v[58:59], v[66:67]
	v_add_f32_e32 v2, 1.0, v2
	v_rcp_f32_e32 v60, v2
	v_mul_f32_e32 v2, 0xbfb8aa3b, v53
	v_exp_f32_e32 v2, v2
	s_nop 0
	v_add_f32_e32 v2, 1.0, v2
	v_rcp_f32_e32 v61, v2
	s_nop 0
	v_pk_mul_f32 v[52:53], v[60:61], v[52:53]
	s_nop 0
	v_pk_mul_f32 v[52:53], v[52:53], v[56:57]
	v_lshlrev_b32_e32 v56, 16, v129
	v_mul_f32_e32 v2, 0xbfb8aa3b, v56
	v_exp_f32_e32 v2, v2
	v_and_b32_e32 v57, 0xffff0000, v129
	v_cvt_pk_bf16_f32 v52, v52, v53
	v_add_f32_e32 v2, 1.0, v2
	v_rcp_f32_e32 v60, v2
	v_mul_f32_e32 v2, 0xbfb8aa3b, v57
	v_exp_f32_e32 v2, v2
	s_nop 0
	v_add_f32_e32 v2, 1.0, v2
	v_rcp_f32_e32 v61, v2
	s_nop 0
	v_pk_mul_f32 v[56:57], v[60:61], v[56:57]
	s_nop 0
	v_pk_mul_f32 v[56:57], v[56:57], v[58:59]
	s_nop 0
	v_cvt_pk_bf16_f32 v53, v56, v57
	v_lshlrev_b32_e32 v56, 16, v130
	v_mul_f32_e32 v2, 0xbfb8aa3b, v56
	v_exp_f32_e32 v2, v2
	v_and_b32_e32 v57, 0xffff0000, v130
	v_add_f32_e32 v2, 1.0, v2
	v_rcp_f32_e32 v58, v2
	v_mul_f32_e32 v2, 0xbfb8aa3b, v57
	v_exp_f32_e32 v2, v2
	s_nop 0
	v_add_f32_e32 v2, 1.0, v2
	v_rcp_f32_e32 v59, v2
	s_nop 0
	v_pk_mul_f32 v[56:57], v[58:59], v[56:57]
	s_nop 0
	v_pk_mul_f32 v[54:55], v[56:57], v[54:55]
	v_lshlrev_b32_e32 v56, 16, v131
	v_mul_f32_e32 v2, 0xbfb8aa3b, v56
	v_exp_f32_e32 v2, v2
	v_and_b32_e32 v57, 0xffff0000, v131
	v_cvt_pk_bf16_f32 v54, v54, v55
	v_add_f32_e32 v2, 1.0, v2
	v_rcp_f32_e32 v58, v2
	v_mul_f32_e32 v2, 0xbfb8aa3b, v57
	v_exp_f32_e32 v2, v2
	s_nop 0
	v_add_f32_e32 v2, 1.0, v2
	v_rcp_f32_e32 v59, v2
	s_nop 0
	v_pk_mul_f32 v[56:57], v[58:59], v[56:57]
	s_nop 0
	v_pk_mul_f32 v[56:57], v[56:57], v[64:65]
	s_nop 0
	v_cvt_pk_bf16_f32 v55, v56, v57
	v_add_co_u32_e32 v56, vcc, 0x6000, v62
	s_nop 1
	v_addc_co_u32_e32 v57, vcc, 0, v63, vcc
	global_store_dwordx4 v[56:57], v[52:55], off
	s_waitcnt lgkmcnt(0)
	s_barrier
